# qk-norm/rope phase v3: 16-byte loads/stores (3+3 per row), DPP rotate-half and row sums, cos/sin LDS table
# speedup vs baseline: 1.0199x; 1.0046x over previous
; __device__ __forceinline__ void qknorm_phase(const Params& p, int ja, int tid, int bid) {
;   const int lane = tid & 63, wid = tid >> 6;
;   u16* QKV = (u16*)(p.ws + OFF_S);
;   u16* KB = (u16*)(p.ws + OFF_KB);
;   u16* VB = (u16*)(p.ws + OFF_VB);
;   const float qg1 = p.in[32][(size_t)ja * 128 + lane], qg2 = p.in[32][(size_t)ja * 128 + 64 + lane];
;   const float kg1 = p.in[33][(size_t)ja * 128 + lane], kg2 = p.in[33][(size_t)ja * 128 + 64 + lane];
;   const float invf = exp2f(-(float)(lane & 31) * (13.287712379549449f / 32.f));
;   for (int row = bid * 8 + wid; row < MT; row += gridDim.x * 8) {
;     const bool lat = row < ML;
;     const int t = lat ? (row & 4095) : ((row - ML) & 255);
;     const int b = lat ? (row >> 12) : ((row - ML) >> 8);
;     const int key = lat ? CTXL + t : t;
;     float cs = 1.f, sn = 0.f;
;     if (lat) { const float pos = (float)(lane < 32 ? (t >> 6) : (t & 63)); sincosf(pos * invf, &sn, &cs); }
;     u16* qr = QKV + (size_t)row * 1536;
;     u16* kdst = KB + ((size_t)(b * 2) * NKEY + key) * 128;
;     unsigned xr1[10], xr2[10];
; #pragma unroll
;     for (int hs = 0; hs < 10; ++hs) { xr1[hs] = qr[hs * 128 + lane]; xr2[hs] = qr[hs * 128 + 64 + lane]; }
;     const u32x2 vraw = *(const u32x2*)(qr + 1280 + lane * 4);
.LBB0_179:
	s_andn2_b64 vcc, exec, s[0:1]
	s_cbranch_vccnz .LBB0_260
	v_writelane_b32 v255, s84, 55
	s_cmp_lt_i32 s64, 11
	s_mov_b64 s[0:1], -1
	v_writelane_b32 v255, s85, 56
	v_writelane_b32 v255, s86, 57
	v_writelane_b32 v255, s87, 58
	s_mov_b64 s[54:55], s[78:79]
	s_mov_b32 s31, s89
	s_cbranch_scc1 .LBB0_230
	s_cmp_gt_i32 s64, 11
	s_cbranch_scc0 .LBB0_216
	v_ashrrev_i32_e32 v0, 6, v208
	v_lshl_add_u32 v16, s62, 3, v0
	s_mov_b32 s0, 0x8800
	v_cmp_gt_i32_e32 vcc, s0, v16
	s_and_saveexec_b64 s[18:19], vcc
	s_cbranch_execz .LBB0_215
	s_mov_b32 s6, 0
.Lq3_tab:
	s_lshl_b32 s0, s6, 9
	v_add_u32_e32 v97, s0, v203
	v_and_b32_e32 v0, 31, v97
	v_lshrrev_b32_e32 v1, 5, v97
	v_cvt_f32_u32_e32 v0, v0
	v_mul_f32_e32 v0, 0xbed49a78, v0
	v_exp_f32_e32 v0, v0
	v_cvt_f32_u32_e32 v7, v1
	v_mul_f32_e32 v7, v0, v7
	v_mul_f32_e32 v8, 0x3f22f983, v7
	v_rndne_f32_e32 v10, v8
	v_cvt_i32_f32_e32 v9, v10
	v_fmamk_f32 v8, v10, 0xbfc90fda, v7
	v_fmac_f32_e32 v8, 0xb3a22168, v10
	v_fmac_f32_e32 v8, 0xa7c234c4, v10
	v_mul_f32_e32 v10, v8, v8
	v_mov_b32_e32 v11, 0x3c0881c4
	v_fmamk_f32 v11, v10, 0xb94c1982, v11
	v_fmaak_f32 v11, v10, v11, 0xbe2aaa9d
	v_mul_f32_e32 v11, v10, v11
	v_fmac_f32_e32 v8, v8, v11
	v_mov_b32_e32 v11, 0xbab64f3b
	v_fmamk_f32 v11, v10, 0x37d75334, v11
	v_fmaak_f32 v11, v10, v11, 0x3d2aabf7
	v_fmaak_f32 v11, v10, v11, 0xbf000004
	v_fma_f32 v10, v10, v11, 1.0
	v_lshlrev_b32_e32 v11, 30, v9
	v_and_b32_e32 v9, 1, v9
	v_cmp_eq_u32_e64 s[0:1], 0, v9
	s_brev_b32 s4, 1
	s_nop 0
	v_cndmask_b32_e64 v9, v10, v8, s[0:1]
	v_xor_b32_e32 v8, 0x80000000, v8
	v_cndmask_b32_e64 v8, v8, v10, s[0:1]
	v_bitop3_b32 v9, v9, v11, s4 bitop3:0x78
	v_bitop3_b32 v8, v8, v11, s4 bitop3:0x78
	v_lshlrev_b32_e32 v98, 2, v97
	ds_write_b32 v98, v8
	ds_write_b32 v98, v9 offset:8192
	s_add_u32 s6, s6, 1
	s_cmp_lt_u32 s6, 4
	s_cbranch_scc1 .Lq3_tab
	v_and_b32_e32 v2, 63, v203
	v_and_b32_e32 v3, 15, v203
	v_and_b32_e32 v97, 3, v203
	v_lshlrev_b32_e32 v4, 5, v97
	v_bfe_u32 v8, v203, 2, 1
	v_lshlrev_b32_e32 v5, 4, v2
	v_bfe_u32 v97, v203, 3, 1
	v_mov_b32_e32 v7, 1.0
	v_cmp_eq_u32_e32 vcc, 0, v97
	s_nop 1
	v_mov_b32_e32 v98, -1.0
	v_cndmask_b32_e32 v7, v7, v98, vcc
	v_readlane_b32 s4, v254, 35
	v_readlane_b32 s5, v254, 36
	v_readlane_b32 s6, v254, 37
	v_readlane_b32 s7, v254, 38
	s_lshl_b32 s0, s72, 9
	s_add_u32 s4, s4, s0
	s_addc_u32 s5, s5, 0
	s_add_u32 s6, s6, s0
	s_addc_u32 s7, s7, 0
	v_lshlrev_b32_e32 v97, 5, v3
	global_load_dwordx4 v[16:19], v97, s[4:5]
	global_load_dwordx4 v[20:23], v97, s[4:5] offset:16
	global_load_dwordx4 v[24:27], v97, s[6:7]
	global_load_dwordx4 v[28:31], v97, s[6:7] offset:16
	v_bfe_u32 v97, v203, 4, 1
	v_mul_u32_u24_e32 v97, 0x110000, v97
	v_lshl_add_u32 v6, v3, 4, v97
	v_bfe_u32 v97, v203, 5, 1
	s_mov_b32 s0, 0x1100000
	v_mul_lo_u32 v97, v97, s0
	v_add_u32_e32 v6, v6, v97
	v_readlane_b32 s24, v253, 13
	v_readlane_b32 s25, v253, 14
	s_mov_b32 s22, 0
	s_mov_b32 s23, -1
	s_waitcnt vmcnt(0) lgkmcnt(0)
	s_barrier
	v_lshrrev_b32_e32 v97, 6, v203
	s_nop 0
	v_readfirstlane_b32 s0, v97
	s_lshl_b32 s6, s62, 3
	s_add_u32 s6, s6, s0
	s_lshl_b32 s21, s71, 3
	s_mul_i32 s0, s6, 0xc00
	s_add_u32 s8, s92, s0
	s_addc_u32 s9, s93, 0
	global_load_dwordx4 v[32:35], v5, s[8:9] offset:0
	global_load_dwordx4 v[36:39], v5, s[8:9] offset:1024
	global_load_dwordx4 v[40:43], v5, s[8:9] offset:2048
	s_branch .Lq3_main

; __device__ __forceinline__ void qknorm_phase(const Params& p, int ja, int tid, int bid) {
;     ...
;   for (int row = bid * 8 + wid; row < MT; row += gridDim.x * 8) {
;     const bool lat = row < ML;
;     const int t = lat ? (row & 4095) : ((row - ML) & 255);
;     const int b = lat ? (row >> 12) : ((row - ML) >> 8);
;     const int key = lat ? CTXL + t : t;
;     float cs = 1.f, sn = 0.f;
;     if (lat) { const float pos = (float)(lane < 32 ? (t >> 6) : (t & 63)); sincosf(pos * invf, &sn, &cs); }
;     u16* qr = QKV + (size_t)row * 1536;
;     u16* kdst = KB + ((size_t)(b * 2) * NKEY + key) * 128;
;     unsigned xr1[10], xr2[10];
; #pragma unroll
;     for (int hs = 0; hs < 10; ++hs) { xr1[hs] = qr[hs * 128 + lane]; xr2[hs] = qr[hs * 128 + 64 + lane]; }
;     const u32x2 vraw = *(const u32x2*)(qr + 1280 + lane * 4);
.Lq3_main:
.Lq3_row0:
	s_add_u32 s7, s6, s21
	s_cmp_lt_u32 s7, 0x8800
	s_cbranch_scc0 .Lq3_nopf0
	s_mul_i32 s0, s7, 0xc00
	s_add_u32 s10, s92, s0
	s_addc_u32 s11, s93, 0
	global_load_dwordx4 v[44:47], v5, s[10:11] offset:0
	global_load_dwordx4 v[48:51], v5, s[10:11] offset:1024
	global_load_dwordx4 v[52:55], v5, s[10:11] offset:2048
.Lq3_nopf0:
	s_cmp_lt_u32 s6, 0x8000
	s_cselect_b32 s20, 1, 0
	s_and_b32 s0, s6, 0xfff
	s_lshr_b32 s1, s6, 12
	s_sub_u32 s4, s6, 0x8000
	s_and_b32 s5, s4, 0xff
	s_lshr_b32 s4, s4, 8
	s_cmp_eq_u32 s20, 1
	s_cselect_b32 s1, s1, s4
	s_cselect_b32 s5, s0, s5
	s_cselect_b32 s4, 0x100, 0
	s_add_u32 s4, s4, s5
	s_mul_i32 s1, s1, 0x2200
	s_add_u32 s1, s1, s4
	s_lshl_b32 s1, s1, 8
	s_add_u32 s4, s24, s1
	s_addc_u32 s5, s25, 0
	s_cmp_eq_u32 s20, 1
	s_cbranch_scc0 .Lq3_ctx0
	s_lshr_b32 s1, s0, 6
	s_and_b32 s0, s0, 63
	v_mov_b32_e32 v97, s1
	v_mov_b32_e32 v98, s0
	v_cmp_eq_u32_e32 vcc, 0, v8
	s_nop 1
	v_cndmask_b32_e32 v97, v98, v97, vcc
	v_lshl_add_u32 v97, v97, 7, v4
	ds_read_b128 v[56:59], v97
	ds_read_b128 v[60:63], v97 offset:16
	ds_read_b128 v[64:67], v97 offset:8192
	ds_read_b128 v[68:71], v97 offset:8208
	s_branch .Lq3_cs0
.Lq3_ctx0:
	v_mov_b32_e32 v56, 1.0
	v_mov_b32_e32 v64, 0
	v_mov_b32_e32 v57, 1.0
	v_mov_b32_e32 v65, 0
	v_mov_b32_e32 v58, 1.0
	v_mov_b32_e32 v66, 0
	v_mov_b32_e32 v59, 1.0
	v_mov_b32_e32 v67, 0
	v_mov_b32_e32 v60, 1.0
	v_mov_b32_e32 v68, 0
	v_mov_b32_e32 v61, 1.0
	v_mov_b32_e32 v69, 0
	v_mov_b32_e32 v62, 1.0
	v_mov_b32_e32 v70, 0
	v_mov_b32_e32 v63, 1.0
	v_mov_b32_e32 v71, 0
.Lq3_cs0:
	s_cmp_lt_u32 s7, 0x8800
	s_cbranch_scc0 .Lq3_wlast0
	s_waitcnt vmcnt(3) lgkmcnt(0)
	s_branch .Lq3_wd0

; __device__ __forceinline__ u16 f2bf(float x) { return (u16)(cvtpk(x, 0.f) & 0xffffu); }
; #define wave_sum(v) wave_sum_l((v), lane)
; __device__ __forceinline__ void qknorm_phase(const Params& p, int ja, int tid, int bid) {
;     ...
; #pragma unroll
;     for (int hs = 0; hs < 10; ++hs) {
;       const float x1 = __uint_as_float(xr1[hs] << 16), x2 = __uint_as_float(xr2[hs] << 16);
;       const float ss = wave_sum(x1 * x1 + x2 * x2);
;       const float rstd = rsqrtf(ss * (1.f / 128.f) + EPSN);
;       const float y1 = x1 * rstd * (hs < 8 ? qg1 : kg1), y2 = x2 * rstd * (hs < 8 ? qg2 : kg2);
;       const float o1 = y1 * cs - y2 * sn, o2 = y1 * sn + y2 * cs;
;       if (hs < 8) { qr[hs * 128 + lane] = f2bf(o1); qr[hs * 128 + 64 + lane] = f2bf(o2); }
;       else { u16* kd2 = kdst + (size_t)(hs - 8) * NKEY * 128; kd2[lane] = f2bf(o1); kd2[64 + lane] = f2bf(o2); }
.Lq3_wd0:
	v_lshlrev_b32_e32 v72, 16, v32
	v_and_b32_e32 v73, 0xffff0000, v32
	v_lshlrev_b32_e32 v74, 16, v33
	v_and_b32_e32 v75, 0xffff0000, v33
	v_lshlrev_b32_e32 v76, 16, v34
	v_and_b32_e32 v77, 0xffff0000, v34
	v_lshlrev_b32_e32 v78, 16, v35
	v_and_b32_e32 v79, 0xffff0000, v35
	v_mul_f32_e32 v96, v72, v72
	v_fmac_f32_e32 v96, v73, v73
	v_fmac_f32_e32 v96, v74, v74
	v_fmac_f32_e32 v96, v75, v75
	v_fmac_f32_e32 v96, v76, v76
	v_fmac_f32_e32 v96, v77, v77
	v_fmac_f32_e32 v96, v78, v78
	v_fmac_f32_e32 v96, v79, v79
	s_nop 1
	v_add_f32_dpp v96, v96, v96 quad_perm:[1,0,3,2] row_mask:0xf bank_mask:0xf
	s_nop 1
	v_add_f32_dpp v96, v96, v96 quad_perm:[2,3,0,1] row_mask:0xf bank_mask:0xf
	s_nop 1
	v_add_f32_dpp v96, v96, v96 row_half_mirror row_mask:0xf bank_mask:0xf
	s_nop 1
	v_add_f32_dpp v96, v96, v96 row_mirror row_mask:0xf bank_mask:0xf
	s_nop 1
	v_fmamk_f32 v96, v96, 0x3c000000, v202
	v_rsq_f32_e32 v96, v96
	s_nop 0
	v_mul_f32_e32 v80, v96, v72
	v_mul_f32_e32 v81, v96, v73
	v_mul_f32_e32 v82, v96, v74
	v_mul_f32_e32 v83, v96, v75
	v_mul_f32_e32 v84, v96, v76
	v_mul_f32_e32 v85, v96, v77
	v_mul_f32_e32 v86, v96, v78
	v_mul_f32_e32 v87, v96, v79
	v_mul_f32_e32 v80, v16, v80
	v_mul_f32_e32 v81, v17, v81
	v_mul_f32_e32 v82, v18, v82
	v_mul_f32_e32 v83, v19, v83
	v_mul_f32_e32 v84, v20, v84
	v_mul_f32_e32 v85, v21, v85
	v_mul_f32_e32 v86, v22, v86
	v_mul_f32_e32 v87, v23, v87
	s_nop 0
	v_mov_b32_dpp v88, v80 row_ror:8 row_mask:0xf bank_mask:0xf
	v_mov_b32_dpp v89, v81 row_ror:8 row_mask:0xf bank_mask:0xf
	v_mov_b32_dpp v90, v82 row_ror:8 row_mask:0xf bank_mask:0xf
	v_mov_b32_dpp v91, v83 row_ror:8 row_mask:0xf bank_mask:0xf
	v_mov_b32_dpp v92, v84 row_ror:8 row_mask:0xf bank_mask:0xf
	v_mov_b32_dpp v93, v85 row_ror:8 row_mask:0xf bank_mask:0xf
	v_mov_b32_dpp v94, v86 row_ror:8 row_mask:0xf bank_mask:0xf
	v_mov_b32_dpp v95, v87 row_ror:8 row_mask:0xf bank_mask:0xf
	v_mul_f32_e32 v88, v64, v88
	v_mul_f32_e32 v89, v65, v89
	v_mul_f32_e32 v90, v66, v90
	v_mul_f32_e32 v91, v67, v91
	v_mul_f32_e32 v92, v68, v92
	v_mul_f32_e32 v93, v69, v93
	v_mul_f32_e32 v94, v70, v94
	v_mul_f32_e32 v95, v71, v95
	v_mul_f32_e32 v88, v7, v88
	v_mul_f32_e32 v89, v7, v89
	v_mul_f32_e32 v90, v7, v90
	v_mul_f32_e32 v91, v7, v91
	v_mul_f32_e32 v92, v7, v92
	v_mul_f32_e32 v93, v7, v93
	v_mul_f32_e32 v94, v7, v94
	v_mul_f32_e32 v95, v7, v95
	v_fmac_f32_e32 v88, v56, v80
	v_fmac_f32_e32 v89, v57, v81
	v_fmac_f32_e32 v90, v58, v82
	v_fmac_f32_e32 v91, v59, v83
	v_fmac_f32_e32 v92, v60, v84
	v_fmac_f32_e32 v93, v61, v85
	v_fmac_f32_e32 v94, v62, v86
	v_fmac_f32_e32 v95, v63, v87
	v_cvt_pk_bf16_f32 v104, v88, v89
	v_cvt_pk_bf16_f32 v105, v90, v91
	v_cvt_pk_bf16_f32 v106, v92, v93
	v_cvt_pk_bf16_f32 v107, v94, v95
	global_store_dwordx4 v5, v[104:107], s[8:9] offset:0
	v_lshlrev_b32_e32 v72, 16, v36
	v_and_b32_e32 v73, 0xffff0000, v36
	v_lshlrev_b32_e32 v74, 16, v37
	v_and_b32_e32 v75, 0xffff0000, v37
	v_lshlrev_b32_e32 v76, 16, v38
	v_and_b32_e32 v77, 0xffff0000, v38
	v_lshlrev_b32_e32 v78, 16, v39
	v_and_b32_e32 v79, 0xffff0000, v39
	v_mul_f32_e32 v96, v72, v72
	v_fmac_f32_e32 v96, v73, v73
	v_fmac_f32_e32 v96, v74, v74
	v_fmac_f32_e32 v96, v75, v75
	v_fmac_f32_e32 v96, v76, v76
	v_fmac_f32_e32 v96, v77, v77
	v_fmac_f32_e32 v96, v78, v78
	v_fmac_f32_e32 v96, v79, v79
	s_nop 1
	v_add_f32_dpp v96, v96, v96 quad_perm:[1,0,3,2] row_mask:0xf bank_mask:0xf
	s_nop 1
	v_add_f32_dpp v96, v96, v96 quad_perm:[2,3,0,1] row_mask:0xf bank_mask:0xf
	s_nop 1
	v_add_f32_dpp v96, v96, v96 row_half_mirror row_mask:0xf bank_mask:0xf
	s_nop 1
	v_add_f32_dpp v96, v96, v96 row_mirror row_mask:0xf bank_mask:0xf
	s_nop 1
	v_fmamk_f32 v96, v96, 0x3c000000, v202
	v_rsq_f32_e32 v96, v96
	s_nop 0
	v_mul_f32_e32 v80, v96, v72
	v_mul_f32_e32 v81, v96, v73
	v_mul_f32_e32 v82, v96, v74
	v_mul_f32_e32 v83, v96, v75
	v_mul_f32_e32 v84, v96, v76
	v_mul_f32_e32 v85, v96, v77
	v_mul_f32_e32 v86, v96, v78
	v_mul_f32_e32 v87, v96, v79
	v_mul_f32_e32 v80, v16, v80
	v_mul_f32_e32 v81, v17, v81
	v_mul_f32_e32 v82, v18, v82
	v_mul_f32_e32 v83, v19, v83
	v_mul_f32_e32 v84, v20, v84
	v_mul_f32_e32 v85, v21, v85
	v_mul_f32_e32 v86, v22, v86
	v_mul_f32_e32 v87, v23, v87
	s_nop 0
	v_mov_b32_dpp v88, v80 row_ror:8 row_mask:0xf bank_mask:0xf
	v_mov_b32_dpp v89, v81 row_ror:8 row_mask:0xf bank_mask:0xf
	v_mov_b32_dpp v90, v82 row_ror:8 row_mask:0xf bank_mask:0xf
	v_mov_b32_dpp v91, v83 row_ror:8 row_mask:0xf bank_mask:0xf
	v_mov_b32_dpp v92, v84 row_ror:8 row_mask:0xf bank_mask:0xf
; __device__ __forceinline__ u16 f2bf(float x) { return (u16)(cvtpk(x, 0.f) & 0xffffu); }
; #define wave_sum(v) wave_sum_l((v), lane)
; __device__ __forceinline__ void qknorm_phase(const Params& p, int ja, int tid, int bid) {
;     ...
; #pragma unroll
;     for (int hs = 0; hs < 10; ++hs) {
;       const float x1 = __uint_as_float(xr1[hs] << 16), x2 = __uint_as_float(xr2[hs] << 16);
;       const float ss = wave_sum(x1 * x1 + x2 * x2);
;       const float rstd = rsqrtf(ss * (1.f / 128.f) + EPSN);
;       const float y1 = x1 * rstd * (hs < 8 ? qg1 : kg1), y2 = x2 * rstd * (hs < 8 ? qg2 : kg2);
;       const float o1 = y1 * cs - y2 * sn, o2 = y1 * sn + y2 * cs;
;       if (hs < 8) { qr[hs * 128 + lane] = f2bf(o1); qr[hs * 128 + 64 + lane] = f2bf(o2); }
;       else { u16* kd2 = kdst + (size_t)(hs - 8) * NKEY * 128; kd2[lane] = f2bf(o1); kd2[64 + lane] = f2bf(o2); }
;     }
;     *(u32x2*)(VB + ((size_t)(b * 2 + (lane >> 5)) * NKEY + key) * 128 + (lane & 31) * 4) = vraw;
;   }
	v_mov_b32_dpp v93, v85 row_ror:8 row_mask:0xf bank_mask:0xf
	v_mov_b32_dpp v94, v86 row_ror:8 row_mask:0xf bank_mask:0xf
	v_mov_b32_dpp v95, v87 row_ror:8 row_mask:0xf bank_mask:0xf
	v_mul_f32_e32 v88, v64, v88
	v_mul_f32_e32 v89, v65, v89
	v_mul_f32_e32 v90, v66, v90
	v_mul_f32_e32 v91, v67, v91
	v_mul_f32_e32 v92, v68, v92
	v_mul_f32_e32 v93, v69, v93
	v_mul_f32_e32 v94, v70, v94
	v_mul_f32_e32 v95, v71, v95
	v_mul_f32_e32 v88, v7, v88
	v_mul_f32_e32 v89, v7, v89
	v_mul_f32_e32 v90, v7, v90
	v_mul_f32_e32 v91, v7, v91
	v_mul_f32_e32 v92, v7, v92
	v_mul_f32_e32 v93, v7, v93
	v_mul_f32_e32 v94, v7, v94
	v_mul_f32_e32 v95, v7, v95
	v_fmac_f32_e32 v88, v56, v80
	v_fmac_f32_e32 v89, v57, v81
	v_fmac_f32_e32 v90, v58, v82
	v_fmac_f32_e32 v91, v59, v83
	v_fmac_f32_e32 v92, v60, v84
	v_fmac_f32_e32 v93, v61, v85
	v_fmac_f32_e32 v94, v62, v86
	v_fmac_f32_e32 v95, v63, v87
	v_cvt_pk_bf16_f32 v104, v88, v89
	v_cvt_pk_bf16_f32 v105, v90, v91
	v_cvt_pk_bf16_f32 v106, v92, v93
	v_cvt_pk_bf16_f32 v107, v94, v95
	global_store_dwordx4 v5, v[104:107], s[8:9] offset:1024
	v_lshlrev_b32_e32 v72, 16, v40
	v_and_b32_e32 v73, 0xffff0000, v40
	v_lshlrev_b32_e32 v74, 16, v41
	v_and_b32_e32 v75, 0xffff0000, v41
	v_lshlrev_b32_e32 v76, 16, v42
	v_and_b32_e32 v77, 0xffff0000, v42
	v_lshlrev_b32_e32 v78, 16, v43
	v_and_b32_e32 v79, 0xffff0000, v43
	v_mul_f32_e32 v96, v72, v72
	v_fmac_f32_e32 v96, v73, v73
	v_fmac_f32_e32 v96, v74, v74
	v_fmac_f32_e32 v96, v75, v75
	v_fmac_f32_e32 v96, v76, v76
	v_fmac_f32_e32 v96, v77, v77
	v_fmac_f32_e32 v96, v78, v78
	v_fmac_f32_e32 v96, v79, v79
	s_nop 1
	v_add_f32_dpp v96, v96, v96 quad_perm:[1,0,3,2] row_mask:0xf bank_mask:0xf
	s_nop 1
	v_add_f32_dpp v96, v96, v96 quad_perm:[2,3,0,1] row_mask:0xf bank_mask:0xf
	s_nop 1
	v_add_f32_dpp v96, v96, v96 row_half_mirror row_mask:0xf bank_mask:0xf
	s_nop 1
	v_add_f32_dpp v96, v96, v96 row_mirror row_mask:0xf bank_mask:0xf
	s_nop 1
	v_fmamk_f32 v96, v96, 0x3c000000, v202
	v_rsq_f32_e32 v96, v96
	s_nop 0
	v_mul_f32_e32 v80, v96, v72
	v_mul_f32_e32 v81, v96, v73
	v_mul_f32_e32 v82, v96, v74
	v_mul_f32_e32 v83, v96, v75
	v_mul_f32_e32 v84, v96, v76
	v_mul_f32_e32 v85, v96, v77
	v_mul_f32_e32 v86, v96, v78
	v_mul_f32_e32 v87, v96, v79
	v_mul_f32_e32 v80, v24, v80
	v_mul_f32_e32 v81, v25, v81
	v_mul_f32_e32 v82, v26, v82
	v_mul_f32_e32 v83, v27, v83
	v_mul_f32_e32 v84, v28, v84
	v_mul_f32_e32 v85, v29, v85
	v_mul_f32_e32 v86, v30, v86
	v_mul_f32_e32 v87, v31, v87
	s_nop 0
	v_mov_b32_dpp v88, v80 row_ror:8 row_mask:0xf bank_mask:0xf
	v_mov_b32_dpp v89, v81 row_ror:8 row_mask:0xf bank_mask:0xf
	v_mov_b32_dpp v90, v82 row_ror:8 row_mask:0xf bank_mask:0xf
	v_mov_b32_dpp v91, v83 row_ror:8 row_mask:0xf bank_mask:0xf
	v_mov_b32_dpp v92, v84 row_ror:8 row_mask:0xf bank_mask:0xf
	v_mov_b32_dpp v93, v85 row_ror:8 row_mask:0xf bank_mask:0xf
	v_mov_b32_dpp v94, v86 row_ror:8 row_mask:0xf bank_mask:0xf
	v_mov_b32_dpp v95, v87 row_ror:8 row_mask:0xf bank_mask:0xf
	v_mul_f32_e32 v88, v64, v88
	v_mul_f32_e32 v89, v65, v89
	v_mul_f32_e32 v90, v66, v90
	v_mul_f32_e32 v91, v67, v91
	v_mul_f32_e32 v92, v68, v92
	v_mul_f32_e32 v93, v69, v93
	v_mul_f32_e32 v94, v70, v94
	v_mul_f32_e32 v95, v71, v95
	v_mul_f32_e32 v88, v7, v88
	v_mul_f32_e32 v89, v7, v89
	v_mul_f32_e32 v90, v7, v90
	v_mul_f32_e32 v91, v7, v91
	v_mul_f32_e32 v92, v7, v92
	v_mul_f32_e32 v93, v7, v93
	v_mul_f32_e32 v94, v7, v94
	v_mul_f32_e32 v95, v7, v95
	v_fmac_f32_e32 v88, v56, v80
	v_fmac_f32_e32 v89, v57, v81
	v_fmac_f32_e32 v90, v58, v82
	v_fmac_f32_e32 v91, v59, v83
	v_fmac_f32_e32 v92, v60, v84
	v_fmac_f32_e32 v93, v61, v85
	v_fmac_f32_e32 v94, v62, v86
	v_fmac_f32_e32 v95, v63, v87
	v_cvt_pk_bf16_f32 v104, v88, v89
	v_cvt_pk_bf16_f32 v105, v90, v91
	v_cvt_pk_bf16_f32 v106, v92, v93
	v_cvt_pk_bf16_f32 v107, v94, v95
	v_cndmask_b32_e64 v104, v104, v40, s[22:23]
	v_cndmask_b32_e64 v105, v105, v41, s[22:23]
	v_cndmask_b32_e64 v106, v106, v42, s[22:23]
	v_cndmask_b32_e64 v107, v107, v43, s[22:23]
	global_store_dwordx4 v6, v[104:107], s[4:5]
	s_cmp_lt_u32 s7, 0x8800
	s_cbranch_scc0 .Lq3_done
	s_mov_b32 s6, s7
	s_mov_b32 s8, s10
	s_mov_b32 s9, s11
.Lq3_row1:
	s_add_u32 s7, s6, s21
	s_cmp_lt_u32 s7, 0x8800
	s_cbranch_scc0 .Lq3_nopf1
	s_mul_i32 s0, s7, 0xc00
	s_add_u32 s10, s92, s0
	s_addc_u32 s11, s93, 0
	global_load_dwordx4 v[32:35], v5, s[10:11] offset:0
	global_load_dwordx4 v[36:39], v5, s[10:11] offset:1024
	global_load_dwordx4 v[40:43], v5, s[10:11] offset:2048

; __device__ __forceinline__ u16 f2bf(float x) { return (u16)(cvtpk(x, 0.f) & 0xffffu); }
; #define wave_sum(v) wave_sum_l((v), lane)
; __device__ __forceinline__ void qknorm_phase(const Params& p, int ja, int tid, int bid) {
;     ...
; #pragma unroll
;     for (int hs = 0; hs < 10; ++hs) {
;       const float x1 = __uint_as_float(xr1[hs] << 16), x2 = __uint_as_float(xr2[hs] << 16);
;       const float ss = wave_sum(x1 * x1 + x2 * x2);
;       const float rstd = rsqrtf(ss * (1.f / 128.f) + EPSN);
;       const float y1 = x1 * rstd * (hs < 8 ? qg1 : kg1), y2 = x2 * rstd * (hs < 8 ? qg2 : kg2);
;       const float o1 = y1 * cs - y2 * sn, o2 = y1 * sn + y2 * cs;
;       if (hs < 8) { qr[hs * 128 + lane] = f2bf(o1); qr[hs * 128 + 64 + lane] = f2bf(o2); }
;       else { u16* kd2 = kdst + (size_t)(hs - 8) * NKEY * 128; kd2[lane] = f2bf(o1); kd2[64 + lane] = f2bf(o2); }
.Lq3_wd1:
	v_lshlrev_b32_e32 v72, 16, v44
	v_and_b32_e32 v73, 0xffff0000, v44
	v_lshlrev_b32_e32 v74, 16, v45
	v_and_b32_e32 v75, 0xffff0000, v45
	v_lshlrev_b32_e32 v76, 16, v46
	v_and_b32_e32 v77, 0xffff0000, v46
	v_lshlrev_b32_e32 v78, 16, v47
	v_and_b32_e32 v79, 0xffff0000, v47
	v_mul_f32_e32 v96, v72, v72
	v_fmac_f32_e32 v96, v73, v73
	v_fmac_f32_e32 v96, v74, v74
	v_fmac_f32_e32 v96, v75, v75
	v_fmac_f32_e32 v96, v76, v76
	v_fmac_f32_e32 v96, v77, v77
	v_fmac_f32_e32 v96, v78, v78
	v_fmac_f32_e32 v96, v79, v79
	s_nop 1
	v_add_f32_dpp v96, v96, v96 quad_perm:[1,0,3,2] row_mask:0xf bank_mask:0xf
	s_nop 1
	v_add_f32_dpp v96, v96, v96 quad_perm:[2,3,0,1] row_mask:0xf bank_mask:0xf
	s_nop 1
	v_add_f32_dpp v96, v96, v96 row_half_mirror row_mask:0xf bank_mask:0xf
	s_nop 1
	v_add_f32_dpp v96, v96, v96 row_mirror row_mask:0xf bank_mask:0xf
	s_nop 1
	v_fmamk_f32 v96, v96, 0x3c000000, v202
	v_rsq_f32_e32 v96, v96
	s_nop 0
	v_mul_f32_e32 v80, v96, v72
	v_mul_f32_e32 v81, v96, v73
	v_mul_f32_e32 v82, v96, v74
	v_mul_f32_e32 v83, v96, v75
	v_mul_f32_e32 v84, v96, v76
	v_mul_f32_e32 v85, v96, v77
	v_mul_f32_e32 v86, v96, v78
	v_mul_f32_e32 v87, v96, v79
	v_mul_f32_e32 v80, v16, v80
	v_mul_f32_e32 v81, v17, v81
	v_mul_f32_e32 v82, v18, v82
	v_mul_f32_e32 v83, v19, v83
	v_mul_f32_e32 v84, v20, v84
	v_mul_f32_e32 v85, v21, v85
	v_mul_f32_e32 v86, v22, v86
	v_mul_f32_e32 v87, v23, v87
	s_nop 0
	v_mov_b32_dpp v88, v80 row_ror:8 row_mask:0xf bank_mask:0xf
	v_mov_b32_dpp v89, v81 row_ror:8 row_mask:0xf bank_mask:0xf
	v_mov_b32_dpp v90, v82 row_ror:8 row_mask:0xf bank_mask:0xf
	v_mov_b32_dpp v91, v83 row_ror:8 row_mask:0xf bank_mask:0xf
	v_mov_b32_dpp v92, v84 row_ror:8 row_mask:0xf bank_mask:0xf
	v_mov_b32_dpp v93, v85 row_ror:8 row_mask:0xf bank_mask:0xf
	v_mov_b32_dpp v94, v86 row_ror:8 row_mask:0xf bank_mask:0xf
	v_mov_b32_dpp v95, v87 row_ror:8 row_mask:0xf bank_mask:0xf
	v_mul_f32_e32 v88, v64, v88
	v_mul_f32_e32 v89, v65, v89
	v_mul_f32_e32 v90, v66, v90
	v_mul_f32_e32 v91, v67, v91
	v_mul_f32_e32 v92, v68, v92
	v_mul_f32_e32 v93, v69, v93
	v_mul_f32_e32 v94, v70, v94
	v_mul_f32_e32 v95, v71, v95
	v_mul_f32_e32 v88, v7, v88
	v_mul_f32_e32 v89, v7, v89
	v_mul_f32_e32 v90, v7, v90
	v_mul_f32_e32 v91, v7, v91
	v_mul_f32_e32 v92, v7, v92
	v_mul_f32_e32 v93, v7, v93
	v_mul_f32_e32 v94, v7, v94
	v_mul_f32_e32 v95, v7, v95
	v_fmac_f32_e32 v88, v56, v80
	v_fmac_f32_e32 v89, v57, v81
	v_fmac_f32_e32 v90, v58, v82
	v_fmac_f32_e32 v91, v59, v83
	v_fmac_f32_e32 v92, v60, v84
	v_fmac_f32_e32 v93, v61, v85
	v_fmac_f32_e32 v94, v62, v86
	v_fmac_f32_e32 v95, v63, v87
	v_cvt_pk_bf16_f32 v104, v88, v89
	v_cvt_pk_bf16_f32 v105, v90, v91
	v_cvt_pk_bf16_f32 v106, v92, v93
	v_cvt_pk_bf16_f32 v107, v94, v95
	global_store_dwordx4 v5, v[104:107], s[8:9] offset:0
	v_lshlrev_b32_e32 v72, 16, v48
	v_and_b32_e32 v73, 0xffff0000, v48
	v_lshlrev_b32_e32 v74, 16, v49
	v_and_b32_e32 v75, 0xffff0000, v49
	v_lshlrev_b32_e32 v76, 16, v50
	v_and_b32_e32 v77, 0xffff0000, v50
	v_lshlrev_b32_e32 v78, 16, v51
	v_and_b32_e32 v79, 0xffff0000, v51
	v_mul_f32_e32 v96, v72, v72
	v_fmac_f32_e32 v96, v73, v73
	v_fmac_f32_e32 v96, v74, v74
	v_fmac_f32_e32 v96, v75, v75
	v_fmac_f32_e32 v96, v76, v76
	v_fmac_f32_e32 v96, v77, v77
	v_fmac_f32_e32 v96, v78, v78
	v_fmac_f32_e32 v96, v79, v79
	s_nop 1
	v_add_f32_dpp v96, v96, v96 quad_perm:[1,0,3,2] row_mask:0xf bank_mask:0xf
	s_nop 1
	v_add_f32_dpp v96, v96, v96 quad_perm:[2,3,0,1] row_mask:0xf bank_mask:0xf
	s_nop 1
	v_add_f32_dpp v96, v96, v96 row_half_mirror row_mask:0xf bank_mask:0xf
	s_nop 1
	v_add_f32_dpp v96, v96, v96 row_mirror row_mask:0xf bank_mask:0xf
	s_nop 1
	v_fmamk_f32 v96, v96, 0x3c000000, v202
	v_rsq_f32_e32 v96, v96
	s_nop 0
	v_mul_f32_e32 v80, v96, v72
	v_mul_f32_e32 v81, v96, v73
	v_mul_f32_e32 v82, v96, v74
	v_mul_f32_e32 v83, v96, v75
	v_mul_f32_e32 v84, v96, v76
	v_mul_f32_e32 v85, v96, v77
	v_mul_f32_e32 v86, v96, v78
	v_mul_f32_e32 v87, v96, v79
	v_mul_f32_e32 v80, v16, v80
	v_mul_f32_e32 v81, v17, v81
	v_mul_f32_e32 v82, v18, v82
	v_mul_f32_e32 v83, v19, v83
	v_mul_f32_e32 v84, v20, v84
	v_mul_f32_e32 v85, v21, v85
	v_mul_f32_e32 v86, v22, v86
	v_mul_f32_e32 v87, v23, v87
	s_nop 0
	v_mov_b32_dpp v88, v80 row_ror:8 row_mask:0xf bank_mask:0xf
	v_mov_b32_dpp v89, v81 row_ror:8 row_mask:0xf bank_mask:0xf
	v_mov_b32_dpp v90, v82 row_ror:8 row_mask:0xf bank_mask:0xf
	v_mov_b32_dpp v91, v83 row_ror:8 row_mask:0xf bank_mask:0xf
	v_mov_b32_dpp v92, v84 row_ror:8 row_mask:0xf bank_mask:0xf
	v_mov_b32_dpp v93, v85 row_ror:8 row_mask:0xf bank_mask:0xf
	v_mov_b32_dpp v94, v86 row_ror:8 row_mask:0xf bank_mask:0xf
	v_mov_b32_dpp v95, v87 row_ror:8 row_mask:0xf bank_mask:0xf
	v_mul_f32_e32 v88, v64, v88
	v_mul_f32_e32 v89, v65, v89
	v_mul_f32_e32 v90, v66, v90
	v_mul_f32_e32 v91, v67, v91
	v_mul_f32_e32 v92, v68, v92
	v_mul_f32_e32 v93, v69, v93
	v_mul_f32_e32 v94, v70, v94
	v_mul_f32_e32 v95, v71, v95
	v_mul_f32_e32 v88, v7, v88
	v_mul_f32_e32 v89, v7, v89
	v_mul_f32_e32 v90, v7, v90
	v_mul_f32_e32 v91, v7, v91
	v_mul_f32_e32 v92, v7, v92
	v_mul_f32_e32 v93, v7, v93
	v_mul_f32_e32 v94, v7, v94
	v_mul_f32_e32 v95, v7, v95
	v_fmac_f32_e32 v88, v56, v80
	v_fmac_f32_e32 v89, v57, v81
	v_fmac_f32_e32 v90, v58, v82
	v_fmac_f32_e32 v91, v59, v83
	v_fmac_f32_e32 v92, v60, v84
	v_fmac_f32_e32 v93, v61, v85
	v_fmac_f32_e32 v94, v62, v86
	v_fmac_f32_e32 v95, v63, v87
	v_cvt_pk_bf16_f32 v104, v88, v89
	v_cvt_pk_bf16_f32 v105, v90, v91
	v_cvt_pk_bf16_f32 v106, v92, v93
	v_cvt_pk_bf16_f32 v107, v94, v95
	global_store_dwordx4 v5, v[104:107], s[8:9] offset:1024
	v_lshlrev_b32_e32 v72, 16, v52
	v_and_b32_e32 v73, 0xffff0000, v52
	v_lshlrev_b32_e32 v74, 16, v53
; __device__ __forceinline__ u16 f2bf(float x) { return (u16)(cvtpk(x, 0.f) & 0xffffu); }
; #define wave_sum(v) wave_sum_l((v), lane)
; __device__ __forceinline__ void qknorm_phase(const Params& p, int ja, int tid, int bid) {
;     ...
; #pragma unroll
;     for (int hs = 0; hs < 10; ++hs) {
;       const float x1 = __uint_as_float(xr1[hs] << 16), x2 = __uint_as_float(xr2[hs] << 16);
;       const float ss = wave_sum(x1 * x1 + x2 * x2);
;       const float rstd = rsqrtf(ss * (1.f / 128.f) + EPSN);
;       const float y1 = x1 * rstd * (hs < 8 ? qg1 : kg1), y2 = x2 * rstd * (hs < 8 ? qg2 : kg2);
;       const float o1 = y1 * cs - y2 * sn, o2 = y1 * sn + y2 * cs;
;       if (hs < 8) { qr[hs * 128 + lane] = f2bf(o1); qr[hs * 128 + 64 + lane] = f2bf(o2); }
;       else { u16* kd2 = kdst + (size_t)(hs - 8) * NKEY * 128; kd2[lane] = f2bf(o1); kd2[64 + lane] = f2bf(o2); }
;     }
;     *(u32x2*)(VB + ((size_t)(b * 2 + (lane >> 5)) * NKEY + key) * 128 + (lane & 31) * 4) = vraw;
;   }
	v_and_b32_e32 v75, 0xffff0000, v53
	v_lshlrev_b32_e32 v76, 16, v54
	v_and_b32_e32 v77, 0xffff0000, v54
	v_lshlrev_b32_e32 v78, 16, v55
	v_and_b32_e32 v79, 0xffff0000, v55
	v_mul_f32_e32 v96, v72, v72
	v_fmac_f32_e32 v96, v73, v73
	v_fmac_f32_e32 v96, v74, v74
	v_fmac_f32_e32 v96, v75, v75
	v_fmac_f32_e32 v96, v76, v76
	v_fmac_f32_e32 v96, v77, v77
	v_fmac_f32_e32 v96, v78, v78
	v_fmac_f32_e32 v96, v79, v79
	s_nop 1
	v_add_f32_dpp v96, v96, v96 quad_perm:[1,0,3,2] row_mask:0xf bank_mask:0xf
	s_nop 1
	v_add_f32_dpp v96, v96, v96 quad_perm:[2,3,0,1] row_mask:0xf bank_mask:0xf
	s_nop 1
	v_add_f32_dpp v96, v96, v96 row_half_mirror row_mask:0xf bank_mask:0xf
	s_nop 1
	v_add_f32_dpp v96, v96, v96 row_mirror row_mask:0xf bank_mask:0xf
	s_nop 1
	v_fmamk_f32 v96, v96, 0x3c000000, v202
	v_rsq_f32_e32 v96, v96
	s_nop 0
	v_mul_f32_e32 v80, v96, v72
	v_mul_f32_e32 v81, v96, v73
	v_mul_f32_e32 v82, v96, v74
	v_mul_f32_e32 v83, v96, v75
	v_mul_f32_e32 v84, v96, v76
	v_mul_f32_e32 v85, v96, v77
	v_mul_f32_e32 v86, v96, v78
	v_mul_f32_e32 v87, v96, v79
	v_mul_f32_e32 v80, v24, v80
	v_mul_f32_e32 v81, v25, v81
	v_mul_f32_e32 v82, v26, v82
	v_mul_f32_e32 v83, v27, v83
	v_mul_f32_e32 v84, v28, v84
	v_mul_f32_e32 v85, v29, v85
	v_mul_f32_e32 v86, v30, v86
	v_mul_f32_e32 v87, v31, v87
	s_nop 0
	v_mov_b32_dpp v88, v80 row_ror:8 row_mask:0xf bank_mask:0xf
	v_mov_b32_dpp v89, v81 row_ror:8 row_mask:0xf bank_mask:0xf
	v_mov_b32_dpp v90, v82 row_ror:8 row_mask:0xf bank_mask:0xf
	v_mov_b32_dpp v91, v83 row_ror:8 row_mask:0xf bank_mask:0xf
	v_mov_b32_dpp v92, v84 row_ror:8 row_mask:0xf bank_mask:0xf
	v_mov_b32_dpp v93, v85 row_ror:8 row_mask:0xf bank_mask:0xf
	v_mov_b32_dpp v94, v86 row_ror:8 row_mask:0xf bank_mask:0xf
	v_mov_b32_dpp v95, v87 row_ror:8 row_mask:0xf bank_mask:0xf
	v_mul_f32_e32 v88, v64, v88
	v_mul_f32_e32 v89, v65, v89
	v_mul_f32_e32 v90, v66, v90
	v_mul_f32_e32 v91, v67, v91
	v_mul_f32_e32 v92, v68, v92
	v_mul_f32_e32 v93, v69, v93
	v_mul_f32_e32 v94, v70, v94
	v_mul_f32_e32 v95, v71, v95
	v_mul_f32_e32 v88, v7, v88
	v_mul_f32_e32 v89, v7, v89
	v_mul_f32_e32 v90, v7, v90
	v_mul_f32_e32 v91, v7, v91
	v_mul_f32_e32 v92, v7, v92
	v_mul_f32_e32 v93, v7, v93
	v_mul_f32_e32 v94, v7, v94
	v_mul_f32_e32 v95, v7, v95
	v_fmac_f32_e32 v88, v56, v80
	v_fmac_f32_e32 v89, v57, v81
	v_fmac_f32_e32 v90, v58, v82
	v_fmac_f32_e32 v91, v59, v83
	v_fmac_f32_e32 v92, v60, v84
	v_fmac_f32_e32 v93, v61, v85
	v_fmac_f32_e32 v94, v62, v86
	v_fmac_f32_e32 v95, v63, v87
	v_cvt_pk_bf16_f32 v104, v88, v89
	v_cvt_pk_bf16_f32 v105, v90, v91
	v_cvt_pk_bf16_f32 v106, v92, v93
	v_cvt_pk_bf16_f32 v107, v94, v95
	v_cndmask_b32_e64 v104, v104, v52, s[22:23]
	v_cndmask_b32_e64 v105, v105, v53, s[22:23]
	v_cndmask_b32_e64 v106, v106, v54, s[22:23]
	v_cndmask_b32_e64 v107, v107, v55, s[22:23]
	global_store_dwordx4 v6, v[104:107], s[4:5]
	s_cmp_lt_u32 s7, 0x8800
	s_cbranch_scc0 .Lq3_done
	s_mov_b32 s6, s7
	s_mov_b32 s8, s10
	s_mov_b32 s9, s11
	s_branch .Lq3_row0
.Lq3_done:
	s_waitcnt vmcnt(0)
.LBB0_215:
	s_or_b64 exec, exec, s[18:19]
	s_mov_b64 s[0:1], 0
; template <int PASS>
; __device__ __forceinline__ void lru_tile_phase(const Params& p, int jl, int Mrows, char* smem, int tid, int bid) {
;   char* xcL = smem;
;   float* aL = (float*)(smem + 16384);
;   float* uL = (float*)(smem + 16384 + 65536);
;   const u16* P2 = (const u16*)(p.ws + OFF_S);
;   u16* H = (u16*)(p.ws + OFF_LRU_Y);
;   float2* summ = (float2*)(p.ws + OFF_LRU_SUM);
;   const float* carry = (const float*)(p.ws + OFF_LRU_CAR);
;   const u16* Wbd = (const u16*)(p.ws + OFF_WMIX) + 3072 * 1024;
;   const int ntt = Mrows / 64;
;   bf16x8 wb0[8], wb1[8]; float c_ba = 0.f, c_bx = 0.f, c_sp = 0.f; int n_loaded = -1;
;   for (int job = bid; job < ntt * 8; job += gridDim.x) {
;     asm volatile("" : "+v"(tid));
;     const int lane = tid & 63, wid = tid >> 6, l32 = lane & 31, hi = lane >> 5;
;     const int tt = job >> 3, n = job & 7;
;     const bool lat = tt < 512;
;     const int rowbase = lat ? tt * 64 : ML + (tt - 512) * 64;
;     const int sloc = lat ? (tt & 63) * 64 : ((tt - 512) & 3) * 64;
;     const int TT = lat ? SEQL : CTXL;
;     unsigned gv[16]; float carry_in = 0.f;
;     if (PASS == 2) {
;       const int ch = tid & 127, tg = tid >> 7;
; #pragma unroll
;       for (int i = 0; i < 16; ++i) gv[i] = P2[(size_t)(rowbase + tg * 16 + i) * 2048 + n * 128 + ch];
;       if (tid < 256) carry_in = carry[(size_t)(tt * 2 + (tid >> 7)) * 1024 + n * 128 + (tid & 127)];
;     }
;     {
;       const int ch = tid & 127, tg = tid >> 7, t0 = tg * 16;
;       const int col = n * 128 + ch;
;       float cw0 = p.in[18][(size_t)(jl * 4 + 0) * 1024 + col], cw1 = p.in[18][(size_t)(jl * 4 + 1) * 1024 + col];
;       float cw2 = p.in[18][(size_t)(jl * 4 + 2) * 1024 + col], cw3 = p.in[18][(size_t)(jl * 4 + 3) * 1024 + col];
;       const float cb = p.in[19][(size_t)jl * 1024 + col];
;       float xb[19]; unsigned xraw[19];
;       const u16* xsrc = P2 + (size_t)(rowbase - sloc) * 2048 + 1024 + col;
; #pragma unroll
;       for (int i = 0; i < 19; ++i) {
;         const int s = sloc + t0 + i - 2;
;         const int sc = s < 0 ? 0 : (s >= TT ? TT - 1 : s);
;         xraw[i] = xsrc[(size_t)sc * 2048];
;       }
; #pragma unroll
;       for (int i = 0; i < 19; ++i) {
;         const int s = sloc + t0 + i - 2;
;         xb[i] = (s >= 0 && s < TT) ? __uint_as_float(xraw[i] << 16) : 0.f;
;       }
; #pragma unroll
;       for (int i = 0; i < 16; ++i) {
.LBB0_216:
	s_andn2_b64 vcc, exec, s[0:1]
	s_cbranch_vccnz .LBB0_229
	s_lshr_b32 s26, s34, 3
	s_cmp_ge_i32 s62, s26
	s_cbranch_scc1 .LBB0_229
	v_readlane_b32 s0, v253, 1
	v_readlane_b32 s1, v253, 2
	s_sub_u32 s0, s0, 0x138
	s_subb_u32 s1, s1, 0
	s_load_dwordx4 s[36:39], s[0:1], 0x90
	s_load_dwordx2 s[40:41], s[0:1], 0xa8
	s_load_dwordx2 s[44:45], s[0:1], 0xb8
	s_load_dwordx2 s[46:47], s[0:1], 0xc0
	s_load_dwordx2 s[42:43], s[0:1], 0xd0
	s_load_dwordx4 s[48:51], s[0:1], 0xe0
	s_load_dwordx2 s[4:5], s[0:1], 0x128
	s_waitcnt lgkmcnt(0)
	s_lshl_b32 s0, s72, 14
	s_add_u32 s36, s36, s0
	s_addc_u32 s37, s37, 0
	s_lshl_b32 s0, s72, 12
	s_add_u32 s38, s38, s0
	s_addc_u32 s39, s39, 0
	s_add_u32 s40, s40, s0
	s_addc_u32 s41, s41, 0
	s_add_u32 s42, s42, s0
	s_addc_u32 s43, s43, 0
	s_add_u32 s44, s44, s0
	s_addc_u32 s45, s45, 0
	s_add_u32 s46, s46, s0
	s_addc_u32 s47, s47, 0
	s_add_u32 s48, s48, s0
	s_addc_u32 s49, s49, 0
	s_add_u32 s50, s50, s0
	s_addc_u32 s51, s51, 0
	s_add_u32 s22, s4, 0x129dc000
	s_addc_u32 s23, s5, 0
	s_add_u32 s24, s4, 0x1325c000
	s_addc_u32 s25, s5, 0
	s_add_u32 s28, s4, 0x1369c000
	s_addc_u32 s29, s5, 0
	s_add_u32 s18, s4, 0x8e00000
	s_addc_u32 s19, s5, 0
	v_and_b32_e32 v80, 63, v203
	v_lshrrev_b32_e32 v81, 6, v203
	v_and_b32_e32 v236, 31, v203
	v_bfe_u32 v237, v203, 5, 1
	v_lshrrev_b32_e32 v84, 4, v203
	v_and_b32_e32 v99, 15, v203
	v_readfirstlane_b32 s0, v81
	s_and_b32 s1, s0, 3
	s_lshr_b32 s16, s0, 2
	s_mov_b32 s27, s0
	v_lshlrev_b32_e32 v190, 1, v84
	v_lshlrev_b32_e32 v191, 4, v99
	v_or_b32_e32 v195, 0, v190
	v_and_b32_e32 v196, 15, v195
	v_xor_b32_e32 v196, v99, v196
	v_lshlrev_b32_e32 v196, 4, v196
	v_lshl_or_b32 v183, v195, 8, v196
	v_or_b32_e32 v195, 1, v190
	v_and_b32_e32 v196, 15, v195
	v_xor_b32_e32 v196, v99, v196
	v_lshlrev_b32_e32 v196, 4, v196
	v_lshl_or_b32 v184, v195, 8, v196
	v_and_b32_e32 v195, 15, v236
	v_xor_b32_e32 v195, v237, v195
	v_lshlrev_b32_e32 v195, 4, v195
	v_lshl_or_b32 v185, v236, 8, v195
	s_lshl_b32 s4, s1, 5
	v_add_u32_e32 v195, s4, v236
	s_lshl_b32 s5, s16, 6
	v_lshl_add_u32 v196, v237, 2, s5
	v_lshlrev_b32_e32 v196, 7, v196
	v_add_u32_e32 v196, v196, v195
	v_lshlrev_b32_e32 v186, 2, v196
	v_add_u32_e32 v186, 0x4000, v186
	v_add_u32_e32 v187, 0x10000, v186
	v_bfe_u32 v196, v236, 3, 1
	v_cmp_eq_u32_e32 vcc, v196, v237
	v_and_b32_e32 v197, 7, v236
	v_lshrrev_b32_e32 v198, 1, v197
	v_and_b32_e32 v197, 1, v197
	v_lshlrev_b32_e32 v197, 4, v197
	v_mov_b32_e32 v199, 0x3f80
	v_lshlrev_b32_e32 v199, v197, v199
	v_cndmask_b32_e32 v199, 0, v199, vcc
	v_lshrrev_b32_e32 v200, 4, v236
	v_cmp_eq_u32_e32 vcc, 0, v200
	v_cmp_eq_u32_e64 s[4:5], 0, v198
	s_and_b64 vcc, vcc, s[4:5]
	v_cndmask_b32_e32 v172, 0, v199, vcc
	v_cmp_eq_u32_e32 vcc, 0, v200
	v_cmp_eq_u32_e64 s[4:5], 1, v198
	s_and_b64 vcc, vcc, s[4:5]
	v_cndmask_b32_e32 v173, 0, v199, vcc
	v_cmp_eq_u32_e32 vcc, 0, v200
	v_cmp_eq_u32_e64 s[4:5], 2, v198
	s_and_b64 vcc, vcc, s[4:5]
	v_cndmask_b32_e32 v174, 0, v199, vcc
	v_cmp_eq_u32_e32 vcc, 0, v200
	v_cmp_eq_u32_e64 s[4:5], 3, v198
	s_and_b64 vcc, vcc, s[4:5]
	v_cndmask_b32_e32 v175, 0, v199, vcc
	v_cmp_eq_u32_e32 vcc, 1, v200
	v_cmp_eq_u32_e64 s[4:5], 0, v198
	s_and_b64 vcc, vcc, s[4:5]
	v_cndmask_b32_e32 v176, 0, v199, vcc
	v_cmp_eq_u32_e32 vcc, 1, v200
	v_cmp_eq_u32_e64 s[4:5], 1, v198
	s_and_b64 vcc, vcc, s[4:5]
	v_cndmask_b32_e32 v177, 0, v199, vcc
	v_cmp_eq_u32_e32 vcc, 1, v200
	v_cmp_eq_u32_e64 s[4:5], 2, v198
	s_and_b64 vcc, vcc, s[4:5]
	v_cndmask_b32_e32 v178, 0, v199, vcc
	v_cmp_eq_u32_e32 vcc, 1, v200
	v_cmp_eq_u32_e64 s[4:5], 3, v198
	s_and_b64 vcc, vcc, s[4:5]
	v_cndmask_b32_e32 v179, 0, v199, vcc
	v_and_b32_e32 v195, 0x7f, v203
	v_bfe_u32 v196, v203, 7, 1
	v_lshl_or_b32 v196, v196, 13, v195
	v_lshlrev_b32_e32 v188, 2, v196
	v_add_u32_e32 v188, 0x4000, v188
	v_bfe_u32 v196, v203, 7, 1
	v_lshl_or_b32 v194, v196, 10, v195
	v_lshrrev_b32_e32 v195, 3, v203
	v_and_b32_e32 v196, 7, v203
	v_lshlrev_b32_e32 v197, 5, v196
	v_lshl_or_b32 v192, v195, 12, v197
	v_lshl_or_b32 v193, v195, 11, v197
	v_lshlrev_b32_e32 v197, 6, v196
	v_lshl_or_b32 v189, v195, 9, v197
	v_add_u32_e32 v189, 0x14000, v189
	v_mov_b32_e32 v91, 0xbfb8aa3b
	s_mov_b32 s6, s62
	s_mov_b32 s30, -1

; __device__ __forceinline__ float bf2f(u16 x) { return __uint_as_float(((unsigned)x) << 16); }
; __device__ __forceinline__ float fexp(float x) { return __builtin_amdgcn_exp2f(x * 1.4426950408889634f); }
; __device__ __forceinline__ int crow(int r, int hi) { return (r & 3) + 8 * (r >> 2) + 4 * hi; }
; template <int PASS>
; __device__ __forceinline__ void lru_tile_phase(const Params& p, int jl, int Mrows, char* smem, int tid, int bid) {
;     ...
; #pragma unroll
;         for (int r = 0; r < 16; ++r) {
;           const int tok = tb * 32 + crow(r, hi);
;           const float xc = bf2f(*(const u16*)(xcL + swz256(tok, chl >> 3) + (chl & 7) * 2));
;           const float la = c_sp * __builtin_amdgcn_rcpf(1.f + fexp(-(acc0[r] + c_ba)));
;           const float ii = __builtin_amdgcn_rcpf(1.f + fexp(-(acc1[r] + c_bx)));
;           const float av = fexp(la);
;           aL[(dh * 64 + tok) * 128 + chl] = av;
;           uL[(dh * 64 + tok) * 128 + chl] = __builtin_amdgcn_sqrtf(fmaxf(1.f - av * av, 0.f)) * (ii * xc);
;         }
.Llru2_id0_3:
	s_nop 7
	s_nop 7
	v_fma_f32 v80, v0, v91, v180
	v_fma_f32 v81, v16, v91, v181
	v_exp_f32_e32 v80, v80
	v_exp_f32_e32 v81, v81
	v_add_f32_e32 v80, 1.0, v80
	v_add_f32_e32 v81, 1.0, v81
	v_rcp_f32_e32 v80, v80
	v_rcp_f32_e32 v81, v81
	s_nop 0
	v_mul_f32_e32 v80, v182, v80
	v_mul_f32_e32 v81, v81, v32
	v_exp_f32_e32 v80, v80
	s_nop 0
	v_fma_f32 v82, -v80, v80, 1.0
	v_max_f32_e32 v82, 0, v82
	v_sqrt_f32_e32 v82, v82
	ds_write_b32 v186, v80 offset:0
	v_mul_f32_e32 v82, v82, v81
	ds_write_b32 v187, v82 offset:0
	v_fma_f32 v88, v1, v91, v180
	v_fma_f32 v89, v17, v91, v181
	v_exp_f32_e32 v88, v88
	v_exp_f32_e32 v89, v89
	v_add_f32_e32 v88, 1.0, v88
	v_add_f32_e32 v89, 1.0, v89
	v_rcp_f32_e32 v88, v88
	v_rcp_f32_e32 v89, v89
	s_nop 0
	v_mul_f32_e32 v88, v182, v88
	v_mul_f32_e32 v89, v89, v33
	v_exp_f32_e32 v88, v88
	s_nop 0
	v_fma_f32 v90, -v88, v88, 1.0
	v_max_f32_e32 v90, 0, v90
	v_sqrt_f32_e32 v90, v90
	ds_write_b32 v186, v88 offset:512
	v_mul_f32_e32 v90, v90, v89
	ds_write_b32 v187, v90 offset:512
	v_fma_f32 v80, v2, v91, v180
	v_fma_f32 v81, v18, v91, v181
	v_exp_f32_e32 v80, v80
	v_exp_f32_e32 v81, v81
	v_add_f32_e32 v80, 1.0, v80
	v_add_f32_e32 v81, 1.0, v81
	v_rcp_f32_e32 v80, v80
	v_rcp_f32_e32 v81, v81
	s_nop 0
	v_mul_f32_e32 v80, v182, v80
	v_mul_f32_e32 v81, v81, v34
	v_exp_f32_e32 v80, v80
	s_nop 0
	v_fma_f32 v82, -v80, v80, 1.0
	v_max_f32_e32 v82, 0, v82
	v_sqrt_f32_e32 v82, v82
	ds_write_b32 v186, v80 offset:1024
	v_mul_f32_e32 v82, v82, v81
	ds_write_b32 v187, v82 offset:1024
	v_fma_f32 v88, v3, v91, v180
	v_fma_f32 v89, v19, v91, v181
	v_exp_f32_e32 v88, v88
	v_exp_f32_e32 v89, v89
	v_add_f32_e32 v88, 1.0, v88
	v_add_f32_e32 v89, 1.0, v89
	v_rcp_f32_e32 v88, v88
	v_rcp_f32_e32 v89, v89
	s_nop 0
	v_mul_f32_e32 v88, v182, v88
	v_mul_f32_e32 v89, v89, v35
	v_exp_f32_e32 v88, v88
	s_nop 0
	v_fma_f32 v90, -v88, v88, 1.0
	v_max_f32_e32 v90, 0, v90
	v_sqrt_f32_e32 v90, v90
	ds_write_b32 v186, v88 offset:1536
	v_mul_f32_e32 v90, v90, v89
	ds_write_b32 v187, v90 offset:1536
	v_fma_f32 v80, v4, v91, v180
	v_fma_f32 v81, v20, v91, v181
	v_exp_f32_e32 v80, v80
	v_exp_f32_e32 v81, v81
	v_add_f32_e32 v80, 1.0, v80
	v_add_f32_e32 v81, 1.0, v81
	v_rcp_f32_e32 v80, v80
	v_rcp_f32_e32 v81, v81
	s_nop 0
	v_mul_f32_e32 v80, v182, v80
	v_mul_f32_e32 v81, v81, v36
	v_exp_f32_e32 v80, v80
	s_nop 0
	v_fma_f32 v82, -v80, v80, 1.0
	v_max_f32_e32 v82, 0, v82
	v_sqrt_f32_e32 v82, v82
	ds_write_b32 v186, v80 offset:4096
	v_mul_f32_e32 v82, v82, v81
	ds_write_b32 v187, v82 offset:4096
	v_fma_f32 v88, v5, v91, v180
	v_fma_f32 v89, v21, v91, v181
	v_exp_f32_e32 v88, v88
	v_exp_f32_e32 v89, v89
	v_add_f32_e32 v88, 1.0, v88
	v_add_f32_e32 v89, 1.0, v89
	v_rcp_f32_e32 v88, v88
	v_rcp_f32_e32 v89, v89
	s_nop 0
	v_mul_f32_e32 v88, v182, v88
	v_mul_f32_e32 v89, v89, v37
	v_exp_f32_e32 v88, v88
	s_nop 0
	v_fma_f32 v90, -v88, v88, 1.0
	v_max_f32_e32 v90, 0, v90
	v_sqrt_f32_e32 v90, v90
	ds_write_b32 v186, v88 offset:4608
	v_mul_f32_e32 v90, v90, v89
	ds_write_b32 v187, v90 offset:4608
	v_fma_f32 v80, v6, v91, v180
	v_fma_f32 v81, v22, v91, v181
	v_exp_f32_e32 v80, v80
	v_exp_f32_e32 v81, v81
	v_add_f32_e32 v80, 1.0, v80
	v_add_f32_e32 v81, 1.0, v81
	v_rcp_f32_e32 v80, v80
	v_rcp_f32_e32 v81, v81
	s_nop 0
	v_mul_f32_e32 v80, v182, v80
	v_mul_f32_e32 v81, v81, v38
	v_exp_f32_e32 v80, v80
	s_nop 0
	v_fma_f32 v82, -v80, v80, 1.0
	v_max_f32_e32 v82, 0, v82
	v_sqrt_f32_e32 v82, v82
	ds_write_b32 v186, v80 offset:5120
	v_mul_f32_e32 v82, v82, v81
	ds_write_b32 v187, v82 offset:5120
	v_fma_f32 v88, v7, v91, v180
	v_fma_f32 v89, v23, v91, v181
	v_exp_f32_e32 v88, v88
	v_exp_f32_e32 v89, v89
	v_add_f32_e32 v88, 1.0, v88
	v_add_f32_e32 v89, 1.0, v89
	v_rcp_f32_e32 v88, v88
	v_rcp_f32_e32 v89, v89
	s_nop 0
	v_mul_f32_e32 v88, v182, v88
	v_mul_f32_e32 v89, v89, v39
	v_exp_f32_e32 v88, v88
	s_nop 0
	v_fma_f32 v90, -v88, v88, 1.0
	v_max_f32_e32 v90, 0, v90
	v_sqrt_f32_e32 v90, v90
	ds_write_b32 v186, v88 offset:5632
	v_mul_f32_e32 v90, v90, v89
	ds_write_b32 v187, v90 offset:5632
	v_fma_f32 v80, v8, v91, v180
	v_fma_f32 v81, v24, v91, v181
	v_exp_f32_e32 v80, v80
	v_exp_f32_e32 v81, v81
	v_add_f32_e32 v80, 1.0, v80
	v_add_f32_e32 v81, 1.0, v81
	v_rcp_f32_e32 v80, v80
	v_rcp_f32_e32 v81, v81
	s_nop 0
	v_mul_f32_e32 v80, v182, v80
	v_mul_f32_e32 v81, v81, v40
	v_exp_f32_e32 v80, v80
	s_nop 0
	v_fma_f32 v82, -v80, v80, 1.0
	v_max_f32_e32 v82, 0, v82
	v_sqrt_f32_e32 v82, v82
	ds_write_b32 v186, v80 offset:8192
	v_mul_f32_e32 v82, v82, v81
	ds_write_b32 v187, v82 offset:8192
	v_fma_f32 v88, v9, v91, v180
	v_fma_f32 v89, v25, v91, v181
	v_exp_f32_e32 v88, v88
	v_exp_f32_e32 v89, v89
	v_add_f32_e32 v88, 1.0, v88
	v_add_f32_e32 v89, 1.0, v89
	v_rcp_f32_e32 v88, v88
	v_rcp_f32_e32 v89, v89
	s_nop 0
	v_mul_f32_e32 v88, v182, v88
	v_mul_f32_e32 v89, v89, v41
	v_exp_f32_e32 v88, v88
	s_nop 0
	v_fma_f32 v90, -v88, v88, 1.0
	v_max_f32_e32 v90, 0, v90
	v_sqrt_f32_e32 v90, v90
	ds_write_b32 v186, v88 offset:8704
	v_mul_f32_e32 v90, v90, v89
; __device__ __forceinline__ float bf2f(u16 x) { return __uint_as_float(((unsigned)x) << 16); }
; __device__ __forceinline__ float fexp(float x) { return __builtin_amdgcn_exp2f(x * 1.4426950408889634f); }
; __device__ __forceinline__ int crow(int r, int hi) { return (r & 3) + 8 * (r >> 2) + 4 * hi; }
; template <int PASS>
; __device__ __forceinline__ void lru_tile_phase(const Params& p, int jl, int Mrows, char* smem, int tid, int bid) {
;     ...
;         bf16x8 af[8];
; #pragma unroll
;         for (int k16 = 0; k16 < 8; ++k16) af[k16] = *(const bf16x8*)(xcL + swz256(tb * 32 + l32, k16 * 2 + hi));
; #pragma unroll
;         for (int k16 = 0; k16 < 8; ++k16) {
;           acc0 = __builtin_amdgcn_mfma_f32_32x32x16_bf16(af[k16], wb0[k16], acc0, 0, 0, 0);
;           acc1 = __builtin_amdgcn_mfma_f32_32x32x16_bf16(af[k16], wb1[k16], acc1, 0, 0, 0);
;         }
; #pragma unroll
;         for (int r = 0; r < 16; ++r) {
;           const int tok = tb * 32 + crow(r, hi);
;           const float xc = bf2f(*(const u16*)(xcL + swz256(tok, chl >> 3) + (chl & 7) * 2));
;           const float la = c_sp * __builtin_amdgcn_rcpf(1.f + fexp(-(acc0[r] + c_ba)));
;           const float ii = __builtin_amdgcn_rcpf(1.f + fexp(-(acc1[r] + c_bx)));
;           const float av = fexp(la);
;           aL[(dh * 64 + tok) * 128 + chl] = av;
;           uL[(dh * 64 + tok) * 128 + chl] = __builtin_amdgcn_sqrtf(fmaxf(1.f - av * av, 0.f)) * (ii * xc);
;         }
	ds_write_b32 v187, v90 offset:8704
	v_fma_f32 v80, v10, v91, v180
	v_fma_f32 v81, v26, v91, v181
	v_exp_f32_e32 v80, v80
	v_exp_f32_e32 v81, v81
	v_add_f32_e32 v80, 1.0, v80
	v_add_f32_e32 v81, 1.0, v81
	v_rcp_f32_e32 v80, v80
	v_rcp_f32_e32 v81, v81
	s_nop 0
	v_mul_f32_e32 v80, v182, v80
	v_mul_f32_e32 v81, v81, v42
	v_exp_f32_e32 v80, v80
	s_nop 0
	v_fma_f32 v82, -v80, v80, 1.0
	v_max_f32_e32 v82, 0, v82
	v_sqrt_f32_e32 v82, v82
	ds_write_b32 v186, v80 offset:9216
	v_mul_f32_e32 v82, v82, v81
	ds_write_b32 v187, v82 offset:9216
	v_fma_f32 v88, v11, v91, v180
	v_fma_f32 v89, v27, v91, v181
	v_exp_f32_e32 v88, v88
	v_exp_f32_e32 v89, v89
	v_add_f32_e32 v88, 1.0, v88
	v_add_f32_e32 v89, 1.0, v89
	v_rcp_f32_e32 v88, v88
	v_rcp_f32_e32 v89, v89
	s_nop 0
	v_mul_f32_e32 v88, v182, v88
	v_mul_f32_e32 v89, v89, v43
	v_exp_f32_e32 v88, v88
	s_nop 0
	v_fma_f32 v90, -v88, v88, 1.0
	v_max_f32_e32 v90, 0, v90
	v_sqrt_f32_e32 v90, v90
	ds_write_b32 v186, v88 offset:9728
	v_mul_f32_e32 v90, v90, v89
	ds_write_b32 v187, v90 offset:9728
	v_fma_f32 v80, v12, v91, v180
	v_fma_f32 v81, v28, v91, v181
	v_exp_f32_e32 v80, v80
	v_exp_f32_e32 v81, v81
	v_add_f32_e32 v80, 1.0, v80
	v_add_f32_e32 v81, 1.0, v81
	v_rcp_f32_e32 v80, v80
	v_rcp_f32_e32 v81, v81
	s_nop 0
	v_mul_f32_e32 v80, v182, v80
	v_mul_f32_e32 v81, v81, v44
	v_exp_f32_e32 v80, v80
	s_nop 0
	v_fma_f32 v82, -v80, v80, 1.0
	v_max_f32_e32 v82, 0, v82
	v_sqrt_f32_e32 v82, v82
	ds_write_b32 v186, v80 offset:12288
	v_mul_f32_e32 v82, v82, v81
	ds_write_b32 v187, v82 offset:12288
	v_fma_f32 v88, v13, v91, v180
	v_fma_f32 v89, v29, v91, v181
	v_exp_f32_e32 v88, v88
	v_exp_f32_e32 v89, v89
	v_add_f32_e32 v88, 1.0, v88
	v_add_f32_e32 v89, 1.0, v89
	v_rcp_f32_e32 v88, v88
	v_rcp_f32_e32 v89, v89
	s_nop 0
	v_mul_f32_e32 v88, v182, v88
	v_mul_f32_e32 v89, v89, v45
	v_exp_f32_e32 v88, v88
	s_nop 0
	v_fma_f32 v90, -v88, v88, 1.0
	v_max_f32_e32 v90, 0, v90
	v_sqrt_f32_e32 v90, v90
	ds_write_b32 v186, v88 offset:12800
	v_mul_f32_e32 v90, v90, v89
	ds_write_b32 v187, v90 offset:12800
	v_fma_f32 v80, v14, v91, v180
	v_fma_f32 v81, v30, v91, v181
	v_exp_f32_e32 v80, v80
	v_exp_f32_e32 v81, v81
	v_add_f32_e32 v80, 1.0, v80
	v_add_f32_e32 v81, 1.0, v81
	v_rcp_f32_e32 v80, v80
	v_rcp_f32_e32 v81, v81
	s_nop 0
	v_mul_f32_e32 v80, v182, v80
	v_mul_f32_e32 v81, v81, v46
	v_exp_f32_e32 v80, v80
	s_nop 0
	v_fma_f32 v82, -v80, v80, 1.0
	v_max_f32_e32 v82, 0, v82
	v_sqrt_f32_e32 v82, v82
	ds_write_b32 v186, v80 offset:13312
	v_mul_f32_e32 v82, v82, v81
	ds_write_b32 v187, v82 offset:13312
	v_fma_f32 v88, v15, v91, v180
	v_fma_f32 v89, v31, v91, v181
	v_exp_f32_e32 v88, v88
	v_exp_f32_e32 v89, v89
	v_add_f32_e32 v88, 1.0, v88
	v_add_f32_e32 v89, 1.0, v89
	v_rcp_f32_e32 v88, v88
	v_rcp_f32_e32 v89, v89
	s_nop 0
	v_mul_f32_e32 v88, v182, v88
	v_mul_f32_e32 v89, v89, v47
	v_exp_f32_e32 v88, v88
	s_nop 0
	v_fma_f32 v90, -v88, v88, 1.0
	v_max_f32_e32 v90, 0, v90
	v_sqrt_f32_e32 v90, v90
	ds_write_b32 v186, v88 offset:13824
	v_mul_f32_e32 v90, v90, v89
	ds_write_b32 v187, v90 offset:13824
	ds_read_b128 v[48:51], v185 offset:8192
	v_xor_b32_e32 v196, 32, v185
	ds_read_b128 v[52:55], v196 offset:8192
	v_xor_b32_e32 v195, 64, v185
	ds_read_b128 v[56:59], v195 offset:8192
	v_xor_b32_e32 v196, 96, v185
	ds_read_b128 v[60:63], v196 offset:8192
	v_xor_b32_e32 v195, 128, v185
	ds_read_b128 v[64:67], v195 offset:8192
	v_xor_b32_e32 v196, 160, v185
	ds_read_b128 v[68:71], v196 offset:8192
	v_xor_b32_e32 v195, 192, v185
	ds_read_b128 v[72:75], v195 offset:8192
	v_xor_b32_e32 v196, 224, v185
	ds_read_b128 v[76:79], v196 offset:8192
	s_waitcnt lgkmcnt(7)
	v_mfma_f32_32x32x16_bf16 v[0:15], v[48:51], v[140:143], 0
	v_mfma_f32_32x32x16_bf16 v[16:31], v[48:51], v[204:207], 0
	s_waitcnt lgkmcnt(6)
	v_mfma_f32_32x32x16_bf16 v[0:15], v[52:55], v[144:147], v[0:15]
	v_mfma_f32_32x32x16_bf16 v[16:31], v[52:55], v[208:211], v[16:31]
	s_waitcnt lgkmcnt(5)
	v_mfma_f32_32x32x16_bf16 v[0:15], v[56:59], v[148:151], v[0:15]
	v_mfma_f32_32x32x16_bf16 v[16:31], v[56:59], v[212:215], v[16:31]
	s_waitcnt lgkmcnt(4)
	v_mfma_f32_32x32x16_bf16 v[0:15], v[60:63], v[152:155], v[0:15]
	v_mfma_f32_32x32x16_bf16 v[16:31], v[60:63], v[216:219], v[16:31]
	s_waitcnt lgkmcnt(3)
	v_mfma_f32_32x32x16_bf16 v[0:15], v[64:67], v[156:159], v[0:15]
	v_mfma_f32_32x32x16_bf16 v[16:31], v[64:67], v[220:223], v[16:31]
	s_waitcnt lgkmcnt(2)
	v_mfma_f32_32x32x16_bf16 v[0:15], v[68:71], v[160:163], v[0:15]
	v_mfma_f32_32x32x16_bf16 v[16:31], v[68:71], v[224:227], v[16:31]
	s_waitcnt lgkmcnt(1)
	v_mfma_f32_32x32x16_bf16 v[0:15], v[72:75], v[164:167], v[0:15]
	v_mfma_f32_32x32x16_bf16 v[16:31], v[72:75], v[228:231], v[16:31]
	s_waitcnt lgkmcnt(0)
	v_mfma_f32_32x32x16_bf16 v[0:15], v[76:79], v[168:171], v[0:15]
	v_mfma_f32_32x32x16_bf16 v[16:31], v[76:79], v[232:235], v[16:31]
	s_and_b32 s0, s27, 3
	s_cmp_eq_u32 s0, 0
	s_cbranch_scc0 .Llru2_id1_0
	v_mfma_f32_32x32x16_bf16 v[32:47], v[48:51], v[172:175], 0
	v_mfma_f32_32x32x16_bf16 v[32:47], v[52:55], v[176:179], v[32:47]

; __device__ __forceinline__ float bf2f(u16 x) { return __uint_as_float(((unsigned)x) << 16); }
; __device__ __forceinline__ float fexp(float x) { return __builtin_amdgcn_exp2f(x * 1.4426950408889634f); }
; __device__ __forceinline__ int crow(int r, int hi) { return (r & 3) + 8 * (r >> 2) + 4 * hi; }
; template <int PASS>
; __device__ __forceinline__ void lru_tile_phase(const Params& p, int jl, int Mrows, char* smem, int tid, int bid) {
;     ...
; #pragma unroll
;         for (int r = 0; r < 16; ++r) {
;           const int tok = tb * 32 + crow(r, hi);
;           const float xc = bf2f(*(const u16*)(xcL + swz256(tok, chl >> 3) + (chl & 7) * 2));
;           const float la = c_sp * __builtin_amdgcn_rcpf(1.f + fexp(-(acc0[r] + c_ba)));
;           const float ii = __builtin_amdgcn_rcpf(1.f + fexp(-(acc1[r] + c_bx)));
;           const float av = fexp(la);
;           aL[(dh * 64 + tok) * 128 + chl] = av;
;           uL[(dh * 64 + tok) * 128 + chl] = __builtin_amdgcn_sqrtf(fmaxf(1.f - av * av, 0.f)) * (ii * xc);
;         }
.Llru2_id1_3:
	s_nop 7
	s_nop 7
	v_fma_f32 v80, v0, v91, v180
	v_fma_f32 v81, v16, v91, v181
	v_exp_f32_e32 v80, v80
	v_exp_f32_e32 v81, v81
	v_add_f32_e32 v80, 1.0, v80
	v_add_f32_e32 v81, 1.0, v81
	v_rcp_f32_e32 v80, v80
	v_rcp_f32_e32 v81, v81
	s_nop 0
	v_mul_f32_e32 v80, v182, v80
	v_mul_f32_e32 v81, v81, v32
	v_exp_f32_e32 v80, v80
	s_nop 0
	v_fma_f32 v82, -v80, v80, 1.0
	v_max_f32_e32 v82, 0, v82
	v_sqrt_f32_e32 v82, v82
	ds_write_b32 v186, v80 offset:16384
	v_mul_f32_e32 v82, v82, v81
	ds_write_b32 v187, v82 offset:16384
	v_fma_f32 v88, v1, v91, v180
	v_fma_f32 v89, v17, v91, v181
	v_exp_f32_e32 v88, v88
	v_exp_f32_e32 v89, v89
	v_add_f32_e32 v88, 1.0, v88
	v_add_f32_e32 v89, 1.0, v89
	v_rcp_f32_e32 v88, v88
	v_rcp_f32_e32 v89, v89
	s_nop 0
	v_mul_f32_e32 v88, v182, v88
	v_mul_f32_e32 v89, v89, v33
	v_exp_f32_e32 v88, v88
	s_nop 0
	v_fma_f32 v90, -v88, v88, 1.0
	v_max_f32_e32 v90, 0, v90
	v_sqrt_f32_e32 v90, v90
	ds_write_b32 v186, v88 offset:16896
	v_mul_f32_e32 v90, v90, v89
	ds_write_b32 v187, v90 offset:16896
	v_fma_f32 v80, v2, v91, v180
	v_fma_f32 v81, v18, v91, v181
	v_exp_f32_e32 v80, v80
	v_exp_f32_e32 v81, v81
	v_add_f32_e32 v80, 1.0, v80
	v_add_f32_e32 v81, 1.0, v81
	v_rcp_f32_e32 v80, v80
	v_rcp_f32_e32 v81, v81
	s_nop 0
	v_mul_f32_e32 v80, v182, v80
	v_mul_f32_e32 v81, v81, v34
	v_exp_f32_e32 v80, v80
	s_nop 0
	v_fma_f32 v82, -v80, v80, 1.0
	v_max_f32_e32 v82, 0, v82
	v_sqrt_f32_e32 v82, v82
	ds_write_b32 v186, v80 offset:17408
	v_mul_f32_e32 v82, v82, v81
	ds_write_b32 v187, v82 offset:17408
	v_fma_f32 v88, v3, v91, v180
	v_fma_f32 v89, v19, v91, v181
	v_exp_f32_e32 v88, v88
	v_exp_f32_e32 v89, v89
	v_add_f32_e32 v88, 1.0, v88
	v_add_f32_e32 v89, 1.0, v89
	v_rcp_f32_e32 v88, v88
	v_rcp_f32_e32 v89, v89
	s_nop 0
	v_mul_f32_e32 v88, v182, v88
	v_mul_f32_e32 v89, v89, v35
	v_exp_f32_e32 v88, v88
	s_nop 0
	v_fma_f32 v90, -v88, v88, 1.0
	v_max_f32_e32 v90, 0, v90
	v_sqrt_f32_e32 v90, v90
	ds_write_b32 v186, v88 offset:17920
	v_mul_f32_e32 v90, v90, v89
	ds_write_b32 v187, v90 offset:17920
	v_fma_f32 v80, v4, v91, v180
	v_fma_f32 v81, v20, v91, v181
	v_exp_f32_e32 v80, v80
	v_exp_f32_e32 v81, v81
	v_add_f32_e32 v80, 1.0, v80
	v_add_f32_e32 v81, 1.0, v81
	v_rcp_f32_e32 v80, v80
	v_rcp_f32_e32 v81, v81
	s_nop 0
	v_mul_f32_e32 v80, v182, v80
	v_mul_f32_e32 v81, v81, v36
	v_exp_f32_e32 v80, v80
	s_nop 0
	v_fma_f32 v82, -v80, v80, 1.0
	v_max_f32_e32 v82, 0, v82
	v_sqrt_f32_e32 v82, v82
	ds_write_b32 v186, v80 offset:20480
	v_mul_f32_e32 v82, v82, v81
	ds_write_b32 v187, v82 offset:20480
	v_fma_f32 v88, v5, v91, v180
	v_fma_f32 v89, v21, v91, v181
	v_exp_f32_e32 v88, v88
	v_exp_f32_e32 v89, v89
	v_add_f32_e32 v88, 1.0, v88
	v_add_f32_e32 v89, 1.0, v89
	v_rcp_f32_e32 v88, v88
	v_rcp_f32_e32 v89, v89
	s_nop 0
	v_mul_f32_e32 v88, v182, v88
	v_mul_f32_e32 v89, v89, v37
	v_exp_f32_e32 v88, v88
	s_nop 0
	v_fma_f32 v90, -v88, v88, 1.0
	v_max_f32_e32 v90, 0, v90
	v_sqrt_f32_e32 v90, v90
	ds_write_b32 v186, v88 offset:20992
	v_mul_f32_e32 v90, v90, v89
	ds_write_b32 v187, v90 offset:20992
	v_fma_f32 v80, v6, v91, v180
	v_fma_f32 v81, v22, v91, v181
	v_exp_f32_e32 v80, v80
	v_exp_f32_e32 v81, v81
	v_add_f32_e32 v80, 1.0, v80
	v_add_f32_e32 v81, 1.0, v81
	v_rcp_f32_e32 v80, v80
	v_rcp_f32_e32 v81, v81
	s_nop 0
	v_mul_f32_e32 v80, v182, v80
	v_mul_f32_e32 v81, v81, v38
	v_exp_f32_e32 v80, v80
	s_nop 0
	v_fma_f32 v82, -v80, v80, 1.0
	v_max_f32_e32 v82, 0, v82
	v_sqrt_f32_e32 v82, v82
	ds_write_b32 v186, v80 offset:21504
	v_mul_f32_e32 v82, v82, v81
	ds_write_b32 v187, v82 offset:21504
	v_fma_f32 v88, v7, v91, v180
	v_fma_f32 v89, v23, v91, v181
	v_exp_f32_e32 v88, v88
	v_exp_f32_e32 v89, v89
	v_add_f32_e32 v88, 1.0, v88
	v_add_f32_e32 v89, 1.0, v89
	v_rcp_f32_e32 v88, v88
	v_rcp_f32_e32 v89, v89
	s_nop 0
	v_mul_f32_e32 v88, v182, v88
	v_mul_f32_e32 v89, v89, v39
	v_exp_f32_e32 v88, v88
	s_nop 0
	v_fma_f32 v90, -v88, v88, 1.0
	v_max_f32_e32 v90, 0, v90
	v_sqrt_f32_e32 v90, v90
	ds_write_b32 v186, v88 offset:22016
	v_mul_f32_e32 v90, v90, v89
	ds_write_b32 v187, v90 offset:22016
	v_fma_f32 v80, v8, v91, v180
	v_fma_f32 v81, v24, v91, v181
	v_exp_f32_e32 v80, v80
	v_exp_f32_e32 v81, v81
	v_add_f32_e32 v80, 1.0, v80
	v_add_f32_e32 v81, 1.0, v81
	v_rcp_f32_e32 v80, v80
	v_rcp_f32_e32 v81, v81
	s_nop 0
	v_mul_f32_e32 v80, v182, v80
	v_mul_f32_e32 v81, v81, v40
	v_exp_f32_e32 v80, v80
	s_nop 0
	v_fma_f32 v82, -v80, v80, 1.0
	v_max_f32_e32 v82, 0, v82
	v_sqrt_f32_e32 v82, v82
	ds_write_b32 v186, v80 offset:24576
	v_mul_f32_e32 v82, v82, v81
	ds_write_b32 v187, v82 offset:24576
	v_fma_f32 v88, v9, v91, v180
	v_fma_f32 v89, v25, v91, v181
	v_exp_f32_e32 v88, v88
	v_exp_f32_e32 v89, v89
	v_add_f32_e32 v88, 1.0, v88
	v_add_f32_e32 v89, 1.0, v89
	v_rcp_f32_e32 v88, v88
	v_rcp_f32_e32 v89, v89
	s_nop 0
	v_mul_f32_e32 v88, v182, v88
	v_mul_f32_e32 v89, v89, v41
	v_exp_f32_e32 v88, v88
	s_nop 0
	v_fma_f32 v90, -v88, v88, 1.0
	v_max_f32_e32 v90, 0, v90
	v_sqrt_f32_e32 v90, v90
	ds_write_b32 v186, v88 offset:25088
	v_mul_f32_e32 v90, v90, v89
	ds_write_b32 v187, v90 offset:25088
	v_fma_f32 v80, v10, v91, v180
	v_fma_f32 v81, v26, v91, v181
	v_exp_f32_e32 v80, v80
	v_exp_f32_e32 v81, v81
	v_add_f32_e32 v80, 1.0, v80
	v_add_f32_e32 v81, 1.0, v81
	v_rcp_f32_e32 v80, v80
	v_rcp_f32_e32 v81, v81
	s_nop 0
	v_mul_f32_e32 v80, v182, v80
	v_mul_f32_e32 v81, v81, v42
	v_exp_f32_e32 v80, v80
	s_nop 0
	v_fma_f32 v82, -v80, v80, 1.0
	v_max_f32_e32 v82, 0, v82
	v_sqrt_f32_e32 v82, v82
	ds_write_b32 v186, v80 offset:25600
	v_mul_f32_e32 v82, v82, v81
	ds_write_b32 v187, v82 offset:25600
	v_fma_f32 v88, v11, v91, v180
	v_fma_f32 v89, v27, v91, v181
	v_exp_f32_e32 v88, v88
; __device__ __forceinline__ float bf2f(u16 x) { return __uint_as_float(((unsigned)x) << 16); }
; __device__ __forceinline__ float fexp(float x) { return __builtin_amdgcn_exp2f(x * 1.4426950408889634f); }
; __device__ __forceinline__ int crow(int r, int hi) { return (r & 3) + 8 * (r >> 2) + 4 * hi; }
; template <int PASS>
; __device__ __forceinline__ void lru_tile_phase(const Params& p, int jl, int Mrows, char* smem, int tid, int bid) {
;     ...
; #pragma unroll
;         for (int r = 0; r < 16; ++r) {
;           const int tok = tb * 32 + crow(r, hi);
;           const float xc = bf2f(*(const u16*)(xcL + swz256(tok, chl >> 3) + (chl & 7) * 2));
;           const float la = c_sp * __builtin_amdgcn_rcpf(1.f + fexp(-(acc0[r] + c_ba)));
;           const float ii = __builtin_amdgcn_rcpf(1.f + fexp(-(acc1[r] + c_bx)));
;           const float av = fexp(la);
;           aL[(dh * 64 + tok) * 128 + chl] = av;
;           uL[(dh * 64 + tok) * 128 + chl] = __builtin_amdgcn_sqrtf(fmaxf(1.f - av * av, 0.f)) * (ii * xc);
;         }
;       }
;     }
;     __syncthreads();
;     if (tid < 256) {
;       const int dir = tid >> 7, ch = tid & 127;
;       const size_t sidx = (size_t)(tt * 2 + dir) * 1024 + n * 128 + ch;
;       float hst = 0.f, ap = 1.f;
;       if (PASS == 2) hst = carry_in;
;       const float* ap_ = aL + (dir * 64) * 128 + ch;
;       float* up_ = uL + (dir * 64) * 128 + ch;
; #pragma unroll 1
;       for (int i0 = 0; i0 < 64; i0 += 16) {
;         float av[16], uv[16];
; #pragma unroll
;         for (int k = 0; k < 16; ++k) { const int t = dir ? 63 - (i0 + k) : i0 + k; av[k] = ap_[t * 128]; uv[k] = up_[t * 128]; }
; #pragma unroll
;         for (int k = 0; k < 16; ++k) { hst = fmaf(av[k], hst, uv[k]); if (PASS == 1) ap *= av[k]; else uv[k] = hst; }
	v_exp_f32_e32 v89, v89
	v_add_f32_e32 v88, 1.0, v88
	v_add_f32_e32 v89, 1.0, v89
	v_rcp_f32_e32 v88, v88
	v_rcp_f32_e32 v89, v89
	s_nop 0
	v_mul_f32_e32 v88, v182, v88
	v_mul_f32_e32 v89, v89, v43
	v_exp_f32_e32 v88, v88
	s_nop 0
	v_fma_f32 v90, -v88, v88, 1.0
	v_max_f32_e32 v90, 0, v90
	v_sqrt_f32_e32 v90, v90
	ds_write_b32 v186, v88 offset:26112
	v_mul_f32_e32 v90, v90, v89
	ds_write_b32 v187, v90 offset:26112
	v_fma_f32 v80, v12, v91, v180
	v_fma_f32 v81, v28, v91, v181
	v_exp_f32_e32 v80, v80
	v_exp_f32_e32 v81, v81
	v_add_f32_e32 v80, 1.0, v80
	v_add_f32_e32 v81, 1.0, v81
	v_rcp_f32_e32 v80, v80
	v_rcp_f32_e32 v81, v81
	s_nop 0
	v_mul_f32_e32 v80, v182, v80
	v_mul_f32_e32 v81, v81, v44
	v_exp_f32_e32 v80, v80
	s_nop 0
	v_fma_f32 v82, -v80, v80, 1.0
	v_max_f32_e32 v82, 0, v82
	v_sqrt_f32_e32 v82, v82
	ds_write_b32 v186, v80 offset:28672
	v_mul_f32_e32 v82, v82, v81
	ds_write_b32 v187, v82 offset:28672
	v_fma_f32 v88, v13, v91, v180
	v_fma_f32 v89, v29, v91, v181
	v_exp_f32_e32 v88, v88
	v_exp_f32_e32 v89, v89
	v_add_f32_e32 v88, 1.0, v88
	v_add_f32_e32 v89, 1.0, v89
	v_rcp_f32_e32 v88, v88
	v_rcp_f32_e32 v89, v89
	s_nop 0
	v_mul_f32_e32 v88, v182, v88
	v_mul_f32_e32 v89, v89, v45
	v_exp_f32_e32 v88, v88
	s_nop 0
	v_fma_f32 v90, -v88, v88, 1.0
	v_max_f32_e32 v90, 0, v90
	v_sqrt_f32_e32 v90, v90
	ds_write_b32 v186, v88 offset:29184
	v_mul_f32_e32 v90, v90, v89
	ds_write_b32 v187, v90 offset:29184
	v_fma_f32 v80, v14, v91, v180
	v_fma_f32 v81, v30, v91, v181
	v_exp_f32_e32 v80, v80
	v_exp_f32_e32 v81, v81
	v_add_f32_e32 v80, 1.0, v80
	v_add_f32_e32 v81, 1.0, v81
	v_rcp_f32_e32 v80, v80
	v_rcp_f32_e32 v81, v81
	s_nop 0
	v_mul_f32_e32 v80, v182, v80
	v_mul_f32_e32 v81, v81, v46
	v_exp_f32_e32 v80, v80
	s_nop 0
	v_fma_f32 v82, -v80, v80, 1.0
	v_max_f32_e32 v82, 0, v82
	v_sqrt_f32_e32 v82, v82
	ds_write_b32 v186, v80 offset:29696
	v_mul_f32_e32 v82, v82, v81
	ds_write_b32 v187, v82 offset:29696
	v_fma_f32 v88, v15, v91, v180
	v_fma_f32 v89, v31, v91, v181
	v_exp_f32_e32 v88, v88
	v_exp_f32_e32 v89, v89
	v_add_f32_e32 v88, 1.0, v88
	v_add_f32_e32 v89, 1.0, v89
	v_rcp_f32_e32 v88, v88
	v_rcp_f32_e32 v89, v89
	s_nop 0
	v_mul_f32_e32 v88, v182, v88
	v_mul_f32_e32 v89, v89, v47
	v_exp_f32_e32 v88, v88
	s_nop 0
	v_fma_f32 v90, -v88, v88, 1.0
	v_max_f32_e32 v90, 0, v90
	v_sqrt_f32_e32 v90, v90
	ds_write_b32 v186, v88 offset:30208
	v_mul_f32_e32 v90, v90, v89
	ds_write_b32 v187, v90 offset:30208
	s_waitcnt lgkmcnt(0)
	s_barrier
	s_cmp_gt_u32 s27, 3
	s_cbranch_scc1 .Llru2_scan_done
	s_waitcnt vmcnt(0)
	v_mov_b32_e32 v96, v252
	v_add_u32_e32 v195, 0x10000, v188
	s_cmp_gt_u32 s27, 1
	s_cbranch_scc1 .Llru2_scan_bwd
	ds_read2st64_b32 v[0:1], v188 offset0:0 offset1:2
	ds_read2st64_b32 v[2:3], v188 offset0:4 offset1:6
	ds_read2st64_b32 v[4:5], v188 offset0:8 offset1:10
	ds_read2st64_b32 v[6:7], v188 offset0:12 offset1:14
	ds_read2st64_b32 v[8:9], v195 offset0:0 offset1:2
	ds_read2st64_b32 v[10:11], v195 offset0:4 offset1:6
	ds_read2st64_b32 v[12:13], v195 offset0:8 offset1:10
	ds_read2st64_b32 v[14:15], v195 offset0:12 offset1:14
	s_waitcnt lgkmcnt(0)
	ds_read2st64_b32 v[16:17], v188 offset0:16 offset1:18
	ds_read2st64_b32 v[18:19], v188 offset0:20 offset1:22
	ds_read2st64_b32 v[20:21], v188 offset0:24 offset1:26
	ds_read2st64_b32 v[22:23], v188 offset0:28 offset1:30
	ds_read2st64_b32 v[24:25], v195 offset0:16 offset1:18
	ds_read2st64_b32 v[26:27], v195 offset0:20 offset1:22
	ds_read2st64_b32 v[28:29], v195 offset0:24 offset1:26
	ds_read2st64_b32 v[30:31], v195 offset0:28 offset1:30
	v_fma_f32 v96, v0, v96, v8
	v_mov_b32_e32 v32, v96
	v_fma_f32 v96, v1, v96, v9
	v_mov_b32_e32 v33, v96
	v_fma_f32 v96, v2, v96, v10
	v_mov_b32_e32 v34, v96
	v_fma_f32 v96, v3, v96, v11
	v_mov_b32_e32 v35, v96
	v_fma_f32 v96, v4, v96, v12
	v_mov_b32_e32 v36, v96
	v_fma_f32 v96, v5, v96, v13
	v_mov_b32_e32 v37, v96
	v_fma_f32 v96, v6, v96, v14
	v_mov_b32_e32 v38, v96
	v_fma_f32 v96, v7, v96, v15
	v_mov_b32_e32 v39, v96
	ds_write2st64_b32 v195, v32, v33 offset0:0 offset1:2
	ds_write2st64_b32 v195, v34, v35 offset0:4 offset1:6
	ds_write2st64_b32 v195, v36, v37 offset0:8 offset1:10
	ds_write2st64_b32 v195, v38, v39 offset0:12 offset1:14
	s_waitcnt lgkmcnt(0)
	ds_read2st64_b32 v[0:1], v188 offset0:32 offset1:34
	ds_read2st64_b32 v[2:3], v188 offset0:36 offset1:38
	ds_read2st64_b32 v[4:5], v188 offset0:40 offset1:42
	ds_read2st64_b32 v[6:7], v188 offset0:44 offset1:46
	ds_read2st64_b32 v[8:9], v195 offset0:32 offset1:34
	ds_read2st64_b32 v[10:11], v195 offset0:36 offset1:38
	ds_read2st64_b32 v[12:13], v195 offset0:40 offset1:42
	ds_read2st64_b32 v[14:15], v195 offset0:44 offset1:46
	v_fma_f32 v96, v16, v96, v24
	v_mov_b32_e32 v32, v96
	v_fma_f32 v96, v17, v96, v25
	v_mov_b32_e32 v33, v96
	v_fma_f32 v96, v18, v96, v26
	v_mov_b32_e32 v34, v96
	v_fma_f32 v96, v19, v96, v27
	v_mov_b32_e32 v35, v96
	v_fma_f32 v96, v20, v96, v28
	v_mov_b32_e32 v36, v96
	v_fma_f32 v96, v21, v96, v29
	v_mov_b32_e32 v37, v96
	v_fma_f32 v96, v22, v96, v30
	v_mov_b32_e32 v38, v96
	v_fma_f32 v96, v23, v96, v31
	v_mov_b32_e32 v39, v96
	ds_write2st64_b32 v195, v32, v33 offset0:16 offset1:18
	ds_write2st64_b32 v195, v34, v35 offset0:20 offset1:22
	ds_write2st64_b32 v195, v36, v37 offset0:24 offset1:26
	ds_write2st64_b32 v195, v38, v39 offset0:28 offset1:30
	s_waitcnt lgkmcnt(0)
; template <int PASS>
; __device__ __forceinline__ void lru_tile_phase(const Params& p, int jl, int Mrows, char* smem, int tid, int bid) {
;     ...
; #pragma unroll 1
;       for (int i0 = 0; i0 < 64; i0 += 16) {
;         float av[16], uv[16];
; #pragma unroll
;         for (int k = 0; k < 16; ++k) { const int t = dir ? 63 - (i0 + k) : i0 + k; av[k] = ap_[t * 128]; uv[k] = up_[t * 128]; }
; #pragma unroll
;         for (int k = 0; k < 16; ++k) { hst = fmaf(av[k], hst, uv[k]); if (PASS == 1) ap *= av[k]; else uv[k] = hst; }
;         if (PASS == 2) {
; #pragma unroll
;           for (int k = 0; k < 16; ++k) { const int t = dir ? 63 - (i0 + k) : i0 + k; up_[t * 128] = uv[k]; }
;         }
;       }
	ds_read2st64_b32 v[16:17], v188 offset0:48 offset1:50
	ds_read2st64_b32 v[18:19], v188 offset0:52 offset1:54
	ds_read2st64_b32 v[20:21], v188 offset0:56 offset1:58
	ds_read2st64_b32 v[22:23], v188 offset0:60 offset1:62
	ds_read2st64_b32 v[24:25], v195 offset0:48 offset1:50
	ds_read2st64_b32 v[26:27], v195 offset0:52 offset1:54
	ds_read2st64_b32 v[28:29], v195 offset0:56 offset1:58
	ds_read2st64_b32 v[30:31], v195 offset0:60 offset1:62
	v_fma_f32 v96, v0, v96, v8
	v_mov_b32_e32 v32, v96
	v_fma_f32 v96, v1, v96, v9
	v_mov_b32_e32 v33, v96
	v_fma_f32 v96, v2, v96, v10
	v_mov_b32_e32 v34, v96
	v_fma_f32 v96, v3, v96, v11
	v_mov_b32_e32 v35, v96
	v_fma_f32 v96, v4, v96, v12
	v_mov_b32_e32 v36, v96
	v_fma_f32 v96, v5, v96, v13
	v_mov_b32_e32 v37, v96
	v_fma_f32 v96, v6, v96, v14
	v_mov_b32_e32 v38, v96
	v_fma_f32 v96, v7, v96, v15
	v_mov_b32_e32 v39, v96
	ds_write2st64_b32 v195, v32, v33 offset0:32 offset1:34
	ds_write2st64_b32 v195, v34, v35 offset0:36 offset1:38
	ds_write2st64_b32 v195, v36, v37 offset0:40 offset1:42
	ds_write2st64_b32 v195, v38, v39 offset0:44 offset1:46
	s_waitcnt lgkmcnt(0)
	ds_read2st64_b32 v[0:1], v188 offset0:64 offset1:66
	ds_read2st64_b32 v[2:3], v188 offset0:68 offset1:70
	ds_read2st64_b32 v[4:5], v188 offset0:72 offset1:74
	ds_read2st64_b32 v[6:7], v188 offset0:76 offset1:78
	ds_read2st64_b32 v[8:9], v195 offset0:64 offset1:66
	ds_read2st64_b32 v[10:11], v195 offset0:68 offset1:70
	ds_read2st64_b32 v[12:13], v195 offset0:72 offset1:74
	ds_read2st64_b32 v[14:15], v195 offset0:76 offset1:78
	v_fma_f32 v96, v16, v96, v24
	v_mov_b32_e32 v32, v96
	v_fma_f32 v96, v17, v96, v25
	v_mov_b32_e32 v33, v96
	v_fma_f32 v96, v18, v96, v26
	v_mov_b32_e32 v34, v96
	v_fma_f32 v96, v19, v96, v27
	v_mov_b32_e32 v35, v96
	v_fma_f32 v96, v20, v96, v28
	v_mov_b32_e32 v36, v96
	v_fma_f32 v96, v21, v96, v29
	v_mov_b32_e32 v37, v96
	v_fma_f32 v96, v22, v96, v30
	v_mov_b32_e32 v38, v96
	v_fma_f32 v96, v23, v96, v31
	v_mov_b32_e32 v39, v96
	ds_write2st64_b32 v195, v32, v33 offset0:48 offset1:50
	ds_write2st64_b32 v195, v34, v35 offset0:52 offset1:54
	ds_write2st64_b32 v195, v36, v37 offset0:56 offset1:58
	ds_write2st64_b32 v195, v38, v39 offset0:60 offset1:62
	s_waitcnt lgkmcnt(0)
	ds_read2st64_b32 v[16:17], v188 offset0:80 offset1:82
	ds_read2st64_b32 v[18:19], v188 offset0:84 offset1:86
	ds_read2st64_b32 v[20:21], v188 offset0:88 offset1:90
	ds_read2st64_b32 v[22:23], v188 offset0:92 offset1:94
	ds_read2st64_b32 v[24:25], v195 offset0:80 offset1:82
	ds_read2st64_b32 v[26:27], v195 offset0:84 offset1:86
	ds_read2st64_b32 v[28:29], v195 offset0:88 offset1:90
	ds_read2st64_b32 v[30:31], v195 offset0:92 offset1:94
	v_fma_f32 v96, v0, v96, v8
	v_mov_b32_e32 v32, v96
	v_fma_f32 v96, v1, v96, v9
	v_mov_b32_e32 v33, v96
	v_fma_f32 v96, v2, v96, v10
	v_mov_b32_e32 v34, v96
	v_fma_f32 v96, v3, v96, v11
	v_mov_b32_e32 v35, v96
	v_fma_f32 v96, v4, v96, v12
	v_mov_b32_e32 v36, v96
	v_fma_f32 v96, v5, v96, v13
	v_mov_b32_e32 v37, v96
	v_fma_f32 v96, v6, v96, v14
	v_mov_b32_e32 v38, v96
	v_fma_f32 v96, v7, v96, v15
	v_mov_b32_e32 v39, v96
	ds_write2st64_b32 v195, v32, v33 offset0:64 offset1:66
	ds_write2st64_b32 v195, v34, v35 offset0:68 offset1:70
	ds_write2st64_b32 v195, v36, v37 offset0:72 offset1:74
	ds_write2st64_b32 v195, v38, v39 offset0:76 offset1:78
	s_waitcnt lgkmcnt(0)
	ds_read2st64_b32 v[0:1], v188 offset0:96 offset1:98
	ds_read2st64_b32 v[2:3], v188 offset0:100 offset1:102
	ds_read2st64_b32 v[4:5], v188 offset0:104 offset1:106
	ds_read2st64_b32 v[6:7], v188 offset0:108 offset1:110
	ds_read2st64_b32 v[8:9], v195 offset0:96 offset1:98
	ds_read2st64_b32 v[10:11], v195 offset0:100 offset1:102
	ds_read2st64_b32 v[12:13], v195 offset0:104 offset1:106
	ds_read2st64_b32 v[14:15], v195 offset0:108 offset1:110
	v_fma_f32 v96, v16, v96, v24
	v_mov_b32_e32 v32, v96
	v_fma_f32 v96, v17, v96, v25
	v_mov_b32_e32 v33, v96
	v_fma_f32 v96, v18, v96, v26
	v_mov_b32_e32 v34, v96
	v_fma_f32 v96, v19, v96, v27
	v_mov_b32_e32 v35, v96
	v_fma_f32 v96, v20, v96, v28
	v_mov_b32_e32 v36, v96
	v_fma_f32 v96, v21, v96, v29
	v_mov_b32_e32 v37, v96
	v_fma_f32 v96, v22, v96, v30
	v_mov_b32_e32 v38, v96
	v_fma_f32 v96, v23, v96, v31
	v_mov_b32_e32 v39, v96
	ds_write2st64_b32 v195, v32, v33 offset0:80 offset1:82
	ds_write2st64_b32 v195, v34, v35 offset0:84 offset1:86
	ds_write2st64_b32 v195, v36, v37 offset0:88 offset1:90
	ds_write2st64_b32 v195, v38, v39 offset0:92 offset1:94
	s_waitcnt lgkmcnt(0)
	ds_read2st64_b32 v[16:17], v188 offset0:112 offset1:114
	ds_read2st64_b32 v[18:19], v188 offset0:116 offset1:118
	ds_read2st64_b32 v[20:21], v188 offset0:120 offset1:122
	ds_read2st64_b32 v[22:23], v188 offset0:124 offset1:126
	ds_read2st64_b32 v[24:25], v195 offset0:112 offset1:114
	ds_read2st64_b32 v[26:27], v195 offset0:116 offset1:118
	ds_read2st64_b32 v[28:29], v195 offset0:120 offset1:122
	ds_read2st64_b32 v[30:31], v195 offset0:124 offset1:126
	v_fma_f32 v96, v0, v96, v8
	v_mov_b32_e32 v32, v96
	v_fma_f32 v96, v1, v96, v9
	v_mov_b32_e32 v33, v96
	v_fma_f32 v96, v2, v96, v10
	v_mov_b32_e32 v34, v96
	v_fma_f32 v96, v3, v96, v11
	v_mov_b32_e32 v35, v96
	v_fma_f32 v96, v4, v96, v12
	v_mov_b32_e32 v36, v96
	v_fma_f32 v96, v5, v96, v13
	v_mov_b32_e32 v37, v96
	v_fma_f32 v96, v6, v96, v14
	v_mov_b32_e32 v38, v96
	v_fma_f32 v96, v7, v96, v15
	v_mov_b32_e32 v39, v96
	ds_write2st64_b32 v195, v32, v33 offset0:96 offset1:98
	ds_write2st64_b32 v195, v34, v35 offset0:100 offset1:102
	ds_write2st64_b32 v195, v36, v37 offset0:104 offset1:106
	ds_write2st64_b32 v195, v38, v39 offset0:108 offset1:110
	s_waitcnt lgkmcnt(0)
	v_fma_f32 v96, v16, v96, v24
	v_mov_b32_e32 v32, v96
	v_fma_f32 v96, v17, v96, v25
	v_mov_b32_e32 v33, v96
	v_fma_f32 v96, v18, v96, v26
	v_mov_b32_e32 v34, v96
	v_fma_f32 v96, v19, v96, v27
	v_mov_b32_e32 v35, v96
	v_fma_f32 v96, v20, v96, v28
	v_mov_b32_e32 v36, v96
	v_fma_f32 v96, v21, v96, v29
	v_mov_b32_e32 v37, v96
	v_fma_f32 v96, v22, v96, v30
	v_mov_b32_e32 v38, v96
	v_fma_f32 v96, v23, v96, v31
	v_mov_b32_e32 v39, v96
	ds_write2st64_b32 v195, v32, v33 offset0:112 offset1:114
	ds_write2st64_b32 v195, v34, v35 offset0:116 offset1:118
	ds_write2st64_b32 v195, v36, v37 offset0:120 offset1:122
	ds_write2st64_b32 v195, v38, v39 offset0:124 offset1:126
	s_branch .Llru2_scan_store

; template <int PASS>
; __device__ __forceinline__ void lru_tile_phase(const Params& p, int jl, int Mrows, char* smem, int tid, int bid) {
;   char* xcL = smem;
;   float* aL = (float*)(smem + 16384);
;   float* uL = (float*)(smem + 16384 + 65536);
;   const u16* P2 = (const u16*)(p.ws + OFF_S);
;   u16* H = (u16*)(p.ws + OFF_LRU_Y);
;   float2* summ = (float2*)(p.ws + OFF_LRU_SUM);
;   const float* carry = (const float*)(p.ws + OFF_LRU_CAR);
;   const u16* Wbd = (const u16*)(p.ws + OFF_WMIX) + 3072 * 1024;
;   const int ntt = Mrows / 64;
;   bf16x8 wb0[8], wb1[8]; float c_ba = 0.f, c_bx = 0.f, c_sp = 0.f; int n_loaded = -1;
;   for (int job = bid; job < ntt * 8; job += gridDim.x) {
;     asm volatile("" : "+v"(tid));
;     const int lane = tid & 63, wid = tid >> 6, l32 = lane & 31, hi = lane >> 5;
;     const int tt = job >> 3, n = job & 7;
;     const bool lat = tt < 512;
;     const int rowbase = lat ? tt * 64 : ML + (tt - 512) * 64;
;     const int sloc = lat ? (tt & 63) * 64 : ((tt - 512) & 3) * 64;
;     const int TT = lat ? SEQL : CTXL;
;     unsigned gv[16]; float carry_in = 0.f;
;     if (PASS == 2) {
;       const int ch = tid & 127, tg = tid >> 7;
; #pragma unroll
;       for (int i = 0; i < 16; ++i) gv[i] = P2[(size_t)(rowbase + tg * 16 + i) * 2048 + n * 128 + ch];
;       if (tid < 256) carry_in = carry[(size_t)(tt * 2 + (tid >> 7)) * 1024 + n * 128 + (tid & 127)];
;     }
;     {
;       const int ch = tid & 127, tg = tid >> 7, t0 = tg * 16;
;       const int col = n * 128 + ch;
;       float cw0 = p.in[18][(size_t)(jl * 4 + 0) * 1024 + col], cw1 = p.in[18][(size_t)(jl * 4 + 1) * 1024 + col];
;       float cw2 = p.in[18][(size_t)(jl * 4 + 2) * 1024 + col], cw3 = p.in[18][(size_t)(jl * 4 + 3) * 1024 + col];
;       const float cb = p.in[19][(size_t)jl * 1024 + col];
;       float xb[19]; unsigned xraw[19];
;       const u16* xsrc = P2 + (size_t)(rowbase - sloc) * 2048 + 1024 + col;
; #pragma unroll
;       for (int i = 0; i < 19; ++i) {
;         const int s = sloc + t0 + i - 2;
;         const int sc = s < 0 ? 0 : (s >= TT ? TT - 1 : s);
;         xraw[i] = xsrc[(size_t)sc * 2048];
;       }
; #pragma unroll
;       for (int i = 0; i < 19; ++i) {
;         const int s = sloc + t0 + i - 2;
;         xb[i] = (s >= 0 && s < TT) ? __uint_as_float(xraw[i] << 16) : 0.f;
;       }
; #pragma unroll
;       for (int i = 0; i < 16; ++i) {
.LBB0_248:
	s_andn2_b64 vcc, exec, s[0:1]
	s_cbranch_vccnz .LBB0_260
	s_cmpk_gt_i32 s62, 0x10ff
	s_cbranch_scc1 .LBB0_260
	v_readlane_b32 s0, v253, 1
	v_readlane_b32 s1, v253, 2
	s_sub_u32 s0, s0, 0x138
	s_subb_u32 s1, s1, 0
	s_load_dwordx4 s[36:39], s[0:1], 0x90
	s_load_dwordx2 s[40:41], s[0:1], 0xa8
	s_load_dwordx2 s[44:45], s[0:1], 0xb8
	s_load_dwordx2 s[46:47], s[0:1], 0xc0
	s_load_dwordx2 s[42:43], s[0:1], 0xd0
	s_load_dwordx4 s[48:51], s[0:1], 0xe0
	s_load_dwordx2 s[4:5], s[0:1], 0x128
	s_waitcnt lgkmcnt(0)
	s_lshl_b32 s0, s72, 14
	s_add_u32 s36, s36, s0
	s_addc_u32 s37, s37, 0
	s_lshl_b32 s0, s72, 12
	s_add_u32 s38, s38, s0
	s_addc_u32 s39, s39, 0
	s_add_u32 s40, s40, s0
	s_addc_u32 s41, s41, 0
	s_add_u32 s42, s42, s0
	s_addc_u32 s43, s43, 0
	s_add_u32 s44, s44, s0
	s_addc_u32 s45, s45, 0
	s_add_u32 s46, s46, s0
	s_addc_u32 s47, s47, 0
	s_add_u32 s48, s48, s0
	s_addc_u32 s49, s49, 0
	s_add_u32 s50, s50, s0
	s_addc_u32 s51, s51, 0
	s_add_u32 s22, s4, 0x129dc000
	s_addc_u32 s23, s5, 0
	s_add_u32 s24, s4, 0x1325c000
	s_addc_u32 s25, s5, 0
	s_add_u32 s28, s4, 0x1369c000
	s_addc_u32 s29, s5, 0
	s_add_u32 s18, s4, 0x8e00000
	s_addc_u32 s19, s5, 0
	v_and_b32_e32 v80, 63, v203
	v_lshrrev_b32_e32 v81, 6, v203
	v_and_b32_e32 v236, 31, v203
	v_bfe_u32 v237, v203, 5, 1
	v_lshrrev_b32_e32 v84, 4, v203
	v_and_b32_e32 v99, 15, v203
	v_readfirstlane_b32 s0, v81
	s_and_b32 s1, s0, 3
	s_lshr_b32 s16, s0, 2
	s_mov_b32 s27, s0
	v_lshlrev_b32_e32 v190, 1, v84
	v_lshlrev_b32_e32 v191, 4, v99
	v_or_b32_e32 v195, 0, v190
	v_and_b32_e32 v196, 15, v195
	v_xor_b32_e32 v196, v99, v196
	v_lshlrev_b32_e32 v196, 4, v196
	v_lshl_or_b32 v183, v195, 8, v196
	v_or_b32_e32 v195, 1, v190
	v_and_b32_e32 v196, 15, v195
	v_xor_b32_e32 v196, v99, v196
	v_lshlrev_b32_e32 v196, 4, v196
	v_lshl_or_b32 v184, v195, 8, v196
	v_and_b32_e32 v195, 15, v236
	v_xor_b32_e32 v195, v237, v195
	v_lshlrev_b32_e32 v195, 4, v195
	v_lshl_or_b32 v185, v236, 8, v195
	s_lshl_b32 s4, s1, 5
	v_add_u32_e32 v195, s4, v236
	s_lshl_b32 s5, s16, 6
	v_lshl_add_u32 v196, v237, 2, s5
	v_lshlrev_b32_e32 v196, 7, v196
	v_add_u32_e32 v196, v196, v195
	v_lshlrev_b32_e32 v186, 2, v196
	v_add_u32_e32 v186, 0x4000, v186
	v_add_u32_e32 v187, 0x10000, v186
	v_bfe_u32 v196, v236, 3, 1
	v_cmp_eq_u32_e32 vcc, v196, v237
	v_and_b32_e32 v197, 7, v236
	v_lshrrev_b32_e32 v198, 1, v197
	v_and_b32_e32 v197, 1, v197
	v_lshlrev_b32_e32 v197, 4, v197
	v_mov_b32_e32 v199, 0x3f80
	v_lshlrev_b32_e32 v199, v197, v199
	v_cndmask_b32_e32 v199, 0, v199, vcc
	v_lshrrev_b32_e32 v200, 4, v236
	v_cmp_eq_u32_e32 vcc, 0, v200
	v_cmp_eq_u32_e64 s[4:5], 0, v198
	s_and_b64 vcc, vcc, s[4:5]
	v_cndmask_b32_e32 v172, 0, v199, vcc
	v_cmp_eq_u32_e32 vcc, 0, v200
	v_cmp_eq_u32_e64 s[4:5], 1, v198
	s_and_b64 vcc, vcc, s[4:5]
	v_cndmask_b32_e32 v173, 0, v199, vcc
	v_cmp_eq_u32_e32 vcc, 0, v200
	v_cmp_eq_u32_e64 s[4:5], 2, v198
	s_and_b64 vcc, vcc, s[4:5]
	v_cndmask_b32_e32 v174, 0, v199, vcc
	v_cmp_eq_u32_e32 vcc, 0, v200
	v_cmp_eq_u32_e64 s[4:5], 3, v198
	s_and_b64 vcc, vcc, s[4:5]
	v_cndmask_b32_e32 v175, 0, v199, vcc
	v_cmp_eq_u32_e32 vcc, 1, v200
	v_cmp_eq_u32_e64 s[4:5], 0, v198
	s_and_b64 vcc, vcc, s[4:5]
	v_cndmask_b32_e32 v176, 0, v199, vcc
	v_cmp_eq_u32_e32 vcc, 1, v200
	v_cmp_eq_u32_e64 s[4:5], 1, v198
	s_and_b64 vcc, vcc, s[4:5]
	v_cndmask_b32_e32 v177, 0, v199, vcc
	v_cmp_eq_u32_e32 vcc, 1, v200
	v_cmp_eq_u32_e64 s[4:5], 2, v198
	s_and_b64 vcc, vcc, s[4:5]
	v_cndmask_b32_e32 v178, 0, v199, vcc
	v_cmp_eq_u32_e32 vcc, 1, v200
	v_cmp_eq_u32_e64 s[4:5], 3, v198
	s_and_b64 vcc, vcc, s[4:5]
	v_cndmask_b32_e32 v179, 0, v199, vcc
	v_and_b32_e32 v195, 0x7f, v203
	v_bfe_u32 v196, v203, 7, 1
	v_lshl_or_b32 v196, v196, 13, v195
	v_lshlrev_b32_e32 v188, 2, v196
	v_add_u32_e32 v188, 0x4000, v188
	v_bfe_u32 v196, v203, 7, 1
	v_lshl_or_b32 v194, v196, 10, v195
	v_mov_b32_e32 v91, 0xbfb8aa3b
	s_mov_b32 s6, s62
	s_mov_b32 s26, -1

; __device__ __forceinline__ float bf2f(u16 x) { return __uint_as_float(((unsigned)x) << 16); }
; __device__ __forceinline__ float fexp(float x) { return __builtin_amdgcn_exp2f(x * 1.4426950408889634f); }
; __device__ __forceinline__ int crow(int r, int hi) { return (r & 3) + 8 * (r >> 2) + 4 * hi; }
; template <int PASS>
; __device__ __forceinline__ void lru_tile_phase(const Params& p, int jl, int Mrows, char* smem, int tid, int bid) {
;     ...
; #pragma unroll
;         for (int r = 0; r < 16; ++r) {
;           const int tok = tb * 32 + crow(r, hi);
;           const float xc = bf2f(*(const u16*)(xcL + swz256(tok, chl >> 3) + (chl & 7) * 2));
;           const float la = c_sp * __builtin_amdgcn_rcpf(1.f + fexp(-(acc0[r] + c_ba)));
;           const float ii = __builtin_amdgcn_rcpf(1.f + fexp(-(acc1[r] + c_bx)));
;           const float av = fexp(la);
;           aL[(dh * 64 + tok) * 128 + chl] = av;
;           uL[(dh * 64 + tok) * 128 + chl] = __builtin_amdgcn_sqrtf(fmaxf(1.f - av * av, 0.f)) * (ii * xc);
;         }
.Llru1_id1_3:
	s_nop 7
	s_nop 7
	v_fma_f32 v80, v0, v91, v180
	v_fma_f32 v81, v16, v91, v181
	v_exp_f32_e32 v80, v80
	v_exp_f32_e32 v81, v81
	v_add_f32_e32 v80, 1.0, v80
	v_add_f32_e32 v81, 1.0, v81
	v_rcp_f32_e32 v80, v80
	v_rcp_f32_e32 v81, v81
	s_nop 0
	v_mul_f32_e32 v80, v182, v80
	v_mul_f32_e32 v81, v81, v32
	v_exp_f32_e32 v80, v80
	s_nop 0
	v_fma_f32 v82, -v80, v80, 1.0
	v_max_f32_e32 v82, 0, v82
	v_sqrt_f32_e32 v82, v82
	ds_write_b32 v186, v80 offset:16384
	v_mul_f32_e32 v82, v82, v81
	ds_write_b32 v187, v82 offset:16384
	v_fma_f32 v88, v1, v91, v180
	v_fma_f32 v89, v17, v91, v181
	v_exp_f32_e32 v88, v88
	v_exp_f32_e32 v89, v89
	v_add_f32_e32 v88, 1.0, v88
	v_add_f32_e32 v89, 1.0, v89
	v_rcp_f32_e32 v88, v88
	v_rcp_f32_e32 v89, v89
	s_nop 0
	v_mul_f32_e32 v88, v182, v88
	v_mul_f32_e32 v89, v89, v33
	v_exp_f32_e32 v88, v88
	s_nop 0
	v_fma_f32 v90, -v88, v88, 1.0
	v_max_f32_e32 v90, 0, v90
	v_sqrt_f32_e32 v90, v90
	ds_write_b32 v186, v88 offset:16896
	v_mul_f32_e32 v90, v90, v89
	ds_write_b32 v187, v90 offset:16896
	v_fma_f32 v80, v2, v91, v180
	v_fma_f32 v81, v18, v91, v181
	v_exp_f32_e32 v80, v80
	v_exp_f32_e32 v81, v81
	v_add_f32_e32 v80, 1.0, v80
	v_add_f32_e32 v81, 1.0, v81
	v_rcp_f32_e32 v80, v80
	v_rcp_f32_e32 v81, v81
	s_nop 0
	v_mul_f32_e32 v80, v182, v80
	v_mul_f32_e32 v81, v81, v34
	v_exp_f32_e32 v80, v80
	s_nop 0
	v_fma_f32 v82, -v80, v80, 1.0
	v_max_f32_e32 v82, 0, v82
	v_sqrt_f32_e32 v82, v82
	ds_write_b32 v186, v80 offset:17408
	v_mul_f32_e32 v82, v82, v81
	ds_write_b32 v187, v82 offset:17408
	v_fma_f32 v88, v3, v91, v180
	v_fma_f32 v89, v19, v91, v181
	v_exp_f32_e32 v88, v88
	v_exp_f32_e32 v89, v89
	v_add_f32_e32 v88, 1.0, v88
	v_add_f32_e32 v89, 1.0, v89
	v_rcp_f32_e32 v88, v88
	v_rcp_f32_e32 v89, v89
	s_nop 0
	v_mul_f32_e32 v88, v182, v88
	v_mul_f32_e32 v89, v89, v35
	v_exp_f32_e32 v88, v88
	s_nop 0
	v_fma_f32 v90, -v88, v88, 1.0
	v_max_f32_e32 v90, 0, v90
	v_sqrt_f32_e32 v90, v90
	ds_write_b32 v186, v88 offset:17920
	v_mul_f32_e32 v90, v90, v89
	ds_write_b32 v187, v90 offset:17920
	v_fma_f32 v80, v4, v91, v180
	v_fma_f32 v81, v20, v91, v181
	v_exp_f32_e32 v80, v80
	v_exp_f32_e32 v81, v81
	v_add_f32_e32 v80, 1.0, v80
	v_add_f32_e32 v81, 1.0, v81
	v_rcp_f32_e32 v80, v80
	v_rcp_f32_e32 v81, v81
	s_nop 0
	v_mul_f32_e32 v80, v182, v80
	v_mul_f32_e32 v81, v81, v36
	v_exp_f32_e32 v80, v80
	s_nop 0
	v_fma_f32 v82, -v80, v80, 1.0
	v_max_f32_e32 v82, 0, v82
	v_sqrt_f32_e32 v82, v82
	ds_write_b32 v186, v80 offset:20480
	v_mul_f32_e32 v82, v82, v81
	ds_write_b32 v187, v82 offset:20480
	v_fma_f32 v88, v5, v91, v180
	v_fma_f32 v89, v21, v91, v181
	v_exp_f32_e32 v88, v88
	v_exp_f32_e32 v89, v89
	v_add_f32_e32 v88, 1.0, v88
	v_add_f32_e32 v89, 1.0, v89
	v_rcp_f32_e32 v88, v88
	v_rcp_f32_e32 v89, v89
	s_nop 0
	v_mul_f32_e32 v88, v182, v88
	v_mul_f32_e32 v89, v89, v37
	v_exp_f32_e32 v88, v88
	s_nop 0
	v_fma_f32 v90, -v88, v88, 1.0
	v_max_f32_e32 v90, 0, v90
	v_sqrt_f32_e32 v90, v90
	ds_write_b32 v186, v88 offset:20992
	v_mul_f32_e32 v90, v90, v89
	ds_write_b32 v187, v90 offset:20992
	v_fma_f32 v80, v6, v91, v180
	v_fma_f32 v81, v22, v91, v181
	v_exp_f32_e32 v80, v80
	v_exp_f32_e32 v81, v81
	v_add_f32_e32 v80, 1.0, v80
	v_add_f32_e32 v81, 1.0, v81
	v_rcp_f32_e32 v80, v80
	v_rcp_f32_e32 v81, v81
	s_nop 0
	v_mul_f32_e32 v80, v182, v80
	v_mul_f32_e32 v81, v81, v38
	v_exp_f32_e32 v80, v80
	s_nop 0
	v_fma_f32 v82, -v80, v80, 1.0
	v_max_f32_e32 v82, 0, v82
	v_sqrt_f32_e32 v82, v82
	ds_write_b32 v186, v80 offset:21504
	v_mul_f32_e32 v82, v82, v81
	ds_write_b32 v187, v82 offset:21504
	v_fma_f32 v88, v7, v91, v180
	v_fma_f32 v89, v23, v91, v181
	v_exp_f32_e32 v88, v88
	v_exp_f32_e32 v89, v89
	v_add_f32_e32 v88, 1.0, v88
	v_add_f32_e32 v89, 1.0, v89
	v_rcp_f32_e32 v88, v88
	v_rcp_f32_e32 v89, v89
	s_nop 0
	v_mul_f32_e32 v88, v182, v88
	v_mul_f32_e32 v89, v89, v39
	v_exp_f32_e32 v88, v88
	s_nop 0
	v_fma_f32 v90, -v88, v88, 1.0
	v_max_f32_e32 v90, 0, v90
	v_sqrt_f32_e32 v90, v90
	ds_write_b32 v186, v88 offset:22016
	v_mul_f32_e32 v90, v90, v89
	ds_write_b32 v187, v90 offset:22016
	v_fma_f32 v80, v8, v91, v180
	v_fma_f32 v81, v24, v91, v181
	v_exp_f32_e32 v80, v80
	v_exp_f32_e32 v81, v81
	v_add_f32_e32 v80, 1.0, v80
	v_add_f32_e32 v81, 1.0, v81
	v_rcp_f32_e32 v80, v80
	v_rcp_f32_e32 v81, v81
	s_nop 0
	v_mul_f32_e32 v80, v182, v80
	v_mul_f32_e32 v81, v81, v40
	v_exp_f32_e32 v80, v80
	s_nop 0
	v_fma_f32 v82, -v80, v80, 1.0
	v_max_f32_e32 v82, 0, v82
	v_sqrt_f32_e32 v82, v82
	ds_write_b32 v186, v80 offset:24576
	v_mul_f32_e32 v82, v82, v81
	ds_write_b32 v187, v82 offset:24576
	v_fma_f32 v88, v9, v91, v180
	v_fma_f32 v89, v25, v91, v181
	v_exp_f32_e32 v88, v88
	v_exp_f32_e32 v89, v89
	v_add_f32_e32 v88, 1.0, v88
	v_add_f32_e32 v89, 1.0, v89
	v_rcp_f32_e32 v88, v88
	v_rcp_f32_e32 v89, v89
	s_nop 0
	v_mul_f32_e32 v88, v182, v88
	v_mul_f32_e32 v89, v89, v41
	v_exp_f32_e32 v88, v88
	s_nop 0
	v_fma_f32 v90, -v88, v88, 1.0
	v_max_f32_e32 v90, 0, v90
	v_sqrt_f32_e32 v90, v90
	ds_write_b32 v186, v88 offset:25088
	v_mul_f32_e32 v90, v90, v89
	ds_write_b32 v187, v90 offset:25088
	v_fma_f32 v80, v10, v91, v180
	v_fma_f32 v81, v26, v91, v181
	v_exp_f32_e32 v80, v80
	v_exp_f32_e32 v81, v81
	v_add_f32_e32 v80, 1.0, v80
	v_add_f32_e32 v81, 1.0, v81
	v_rcp_f32_e32 v80, v80
	v_rcp_f32_e32 v81, v81
	s_nop 0
	v_mul_f32_e32 v80, v182, v80
	v_mul_f32_e32 v81, v81, v42
	v_exp_f32_e32 v80, v80
	s_nop 0
	v_fma_f32 v82, -v80, v80, 1.0
	v_max_f32_e32 v82, 0, v82
	v_sqrt_f32_e32 v82, v82
	ds_write_b32 v186, v80 offset:25600
	v_mul_f32_e32 v82, v82, v81
	ds_write_b32 v187, v82 offset:25600
	v_fma_f32 v88, v11, v91, v180
	v_fma_f32 v89, v27, v91, v181
	v_exp_f32_e32 v88, v88
; __device__ __forceinline__ float bf2f(u16 x) { return __uint_as_float(((unsigned)x) << 16); }
; __device__ __forceinline__ float fexp(float x) { return __builtin_amdgcn_exp2f(x * 1.4426950408889634f); }
; __device__ __forceinline__ int crow(int r, int hi) { return (r & 3) + 8 * (r >> 2) + 4 * hi; }
; template <int PASS>
; __device__ __forceinline__ void lru_tile_phase(const Params& p, int jl, int Mrows, char* smem, int tid, int bid) {
;     ...
; #pragma unroll
;         for (int r = 0; r < 16; ++r) {
;           const int tok = tb * 32 + crow(r, hi);
;           const float xc = bf2f(*(const u16*)(xcL + swz256(tok, chl >> 3) + (chl & 7) * 2));
;           const float la = c_sp * __builtin_amdgcn_rcpf(1.f + fexp(-(acc0[r] + c_ba)));
;           const float ii = __builtin_amdgcn_rcpf(1.f + fexp(-(acc1[r] + c_bx)));
;           const float av = fexp(la);
;           aL[(dh * 64 + tok) * 128 + chl] = av;
;           uL[(dh * 64 + tok) * 128 + chl] = __builtin_amdgcn_sqrtf(fmaxf(1.f - av * av, 0.f)) * (ii * xc);
;         }
;       }
;     }
;     __syncthreads();
;     if (tid < 256) {
;       const int dir = tid >> 7, ch = tid & 127;
;       const size_t sidx = (size_t)(tt * 2 + dir) * 1024 + n * 128 + ch;
;       float hst = 0.f, ap = 1.f;
;       if (PASS == 2) hst = carry_in;
;       const float* ap_ = aL + (dir * 64) * 128 + ch;
;       float* up_ = uL + (dir * 64) * 128 + ch;
; #pragma unroll 1
;       for (int i0 = 0; i0 < 64; i0 += 16) {
;         float av[16], uv[16];
; #pragma unroll
;         for (int k = 0; k < 16; ++k) { const int t = dir ? 63 - (i0 + k) : i0 + k; av[k] = ap_[t * 128]; uv[k] = up_[t * 128]; }
; #pragma unroll
;         for (int k = 0; k < 16; ++k) { hst = fmaf(av[k], hst, uv[k]); if (PASS == 1) ap *= av[k]; else uv[k] = hst; }
	v_exp_f32_e32 v89, v89
	v_add_f32_e32 v88, 1.0, v88
	v_add_f32_e32 v89, 1.0, v89
	v_rcp_f32_e32 v88, v88
	v_rcp_f32_e32 v89, v89
	s_nop 0
	v_mul_f32_e32 v88, v182, v88
	v_mul_f32_e32 v89, v89, v43
	v_exp_f32_e32 v88, v88
	s_nop 0
	v_fma_f32 v90, -v88, v88, 1.0
	v_max_f32_e32 v90, 0, v90
	v_sqrt_f32_e32 v90, v90
	ds_write_b32 v186, v88 offset:26112
	v_mul_f32_e32 v90, v90, v89
	ds_write_b32 v187, v90 offset:26112
	v_fma_f32 v80, v12, v91, v180
	v_fma_f32 v81, v28, v91, v181
	v_exp_f32_e32 v80, v80
	v_exp_f32_e32 v81, v81
	v_add_f32_e32 v80, 1.0, v80
	v_add_f32_e32 v81, 1.0, v81
	v_rcp_f32_e32 v80, v80
	v_rcp_f32_e32 v81, v81
	s_nop 0
	v_mul_f32_e32 v80, v182, v80
	v_mul_f32_e32 v81, v81, v44
	v_exp_f32_e32 v80, v80
	s_nop 0
	v_fma_f32 v82, -v80, v80, 1.0
	v_max_f32_e32 v82, 0, v82
	v_sqrt_f32_e32 v82, v82
	ds_write_b32 v186, v80 offset:28672
	v_mul_f32_e32 v82, v82, v81
	ds_write_b32 v187, v82 offset:28672
	v_fma_f32 v88, v13, v91, v180
	v_fma_f32 v89, v29, v91, v181
	v_exp_f32_e32 v88, v88
	v_exp_f32_e32 v89, v89
	v_add_f32_e32 v88, 1.0, v88
	v_add_f32_e32 v89, 1.0, v89
	v_rcp_f32_e32 v88, v88
	v_rcp_f32_e32 v89, v89
	s_nop 0
	v_mul_f32_e32 v88, v182, v88
	v_mul_f32_e32 v89, v89, v45
	v_exp_f32_e32 v88, v88
	s_nop 0
	v_fma_f32 v90, -v88, v88, 1.0
	v_max_f32_e32 v90, 0, v90
	v_sqrt_f32_e32 v90, v90
	ds_write_b32 v186, v88 offset:29184
	v_mul_f32_e32 v90, v90, v89
	ds_write_b32 v187, v90 offset:29184
	v_fma_f32 v80, v14, v91, v180
	v_fma_f32 v81, v30, v91, v181
	v_exp_f32_e32 v80, v80
	v_exp_f32_e32 v81, v81
	v_add_f32_e32 v80, 1.0, v80
	v_add_f32_e32 v81, 1.0, v81
	v_rcp_f32_e32 v80, v80
	v_rcp_f32_e32 v81, v81
	s_nop 0
	v_mul_f32_e32 v80, v182, v80
	v_mul_f32_e32 v81, v81, v46
	v_exp_f32_e32 v80, v80
	s_nop 0
	v_fma_f32 v82, -v80, v80, 1.0
	v_max_f32_e32 v82, 0, v82
	v_sqrt_f32_e32 v82, v82
	ds_write_b32 v186, v80 offset:29696
	v_mul_f32_e32 v82, v82, v81
	ds_write_b32 v187, v82 offset:29696
	v_fma_f32 v88, v15, v91, v180
	v_fma_f32 v89, v31, v91, v181
	v_exp_f32_e32 v88, v88
	v_exp_f32_e32 v89, v89
	v_add_f32_e32 v88, 1.0, v88
	v_add_f32_e32 v89, 1.0, v89
	v_rcp_f32_e32 v88, v88
	v_rcp_f32_e32 v89, v89
	s_nop 0
	v_mul_f32_e32 v88, v182, v88
	v_mul_f32_e32 v89, v89, v47
	v_exp_f32_e32 v88, v88
	s_nop 0
	v_fma_f32 v90, -v88, v88, 1.0
	v_max_f32_e32 v90, 0, v90
	v_sqrt_f32_e32 v90, v90
	ds_write_b32 v186, v88 offset:30208
	v_mul_f32_e32 v90, v90, v89
	ds_write_b32 v187, v90 offset:30208
	s_waitcnt lgkmcnt(0)
	s_barrier
	s_cmp_gt_u32 s27, 3
	s_cbranch_scc1 .Llru1_scan_done
	v_mov_b32_e32 v96, 0
	v_mov_b32_e32 v97, 1.0
	v_add_u32_e32 v195, 0x10000, v188
	s_cmp_gt_u32 s27, 1
	s_cbranch_scc1 .Llru1_scan_bwd
	ds_read2st64_b32 v[0:1], v188 offset0:0 offset1:2
	ds_read2st64_b32 v[2:3], v188 offset0:4 offset1:6
	ds_read2st64_b32 v[4:5], v188 offset0:8 offset1:10
	ds_read2st64_b32 v[6:7], v188 offset0:12 offset1:14
	ds_read2st64_b32 v[8:9], v195 offset0:0 offset1:2
	ds_read2st64_b32 v[10:11], v195 offset0:4 offset1:6
	ds_read2st64_b32 v[12:13], v195 offset0:8 offset1:10
	ds_read2st64_b32 v[14:15], v195 offset0:12 offset1:14
	s_waitcnt lgkmcnt(0)
	ds_read2st64_b32 v[16:17], v188 offset0:16 offset1:18
	ds_read2st64_b32 v[18:19], v188 offset0:20 offset1:22
	ds_read2st64_b32 v[20:21], v188 offset0:24 offset1:26
	ds_read2st64_b32 v[22:23], v188 offset0:28 offset1:30
	ds_read2st64_b32 v[24:25], v195 offset0:16 offset1:18
	ds_read2st64_b32 v[26:27], v195 offset0:20 offset1:22
	ds_read2st64_b32 v[28:29], v195 offset0:24 offset1:26
	ds_read2st64_b32 v[30:31], v195 offset0:28 offset1:30
	v_fma_f32 v96, v0, v96, v8
	v_mul_f32_e32 v97, v97, v0
	v_fma_f32 v96, v1, v96, v9
	v_mul_f32_e32 v97, v97, v1
	v_fma_f32 v96, v2, v96, v10
	v_mul_f32_e32 v97, v97, v2
	v_fma_f32 v96, v3, v96, v11
	v_mul_f32_e32 v97, v97, v3
	v_fma_f32 v96, v4, v96, v12
	v_mul_f32_e32 v97, v97, v4
	v_fma_f32 v96, v5, v96, v13
	v_mul_f32_e32 v97, v97, v5
	v_fma_f32 v96, v6, v96, v14
	v_mul_f32_e32 v97, v97, v6
	v_fma_f32 v96, v7, v96, v15
	v_mul_f32_e32 v97, v97, v7
	s_waitcnt lgkmcnt(0)
	ds_read2st64_b32 v[0:1], v188 offset0:32 offset1:34
	ds_read2st64_b32 v[2:3], v188 offset0:36 offset1:38
	ds_read2st64_b32 v[4:5], v188 offset0:40 offset1:42
	ds_read2st64_b32 v[6:7], v188 offset0:44 offset1:46
	ds_read2st64_b32 v[8:9], v195 offset0:32 offset1:34
	ds_read2st64_b32 v[10:11], v195 offset0:36 offset1:38
	ds_read2st64_b32 v[12:13], v195 offset0:40 offset1:42
	ds_read2st64_b32 v[14:15], v195 offset0:44 offset1:46
	v_fma_f32 v96, v16, v96, v24
	v_mul_f32_e32 v97, v97, v16
	v_fma_f32 v96, v17, v96, v25
	v_mul_f32_e32 v97, v97, v17
	v_fma_f32 v96, v18, v96, v26
	v_mul_f32_e32 v97, v97, v18
	v_fma_f32 v96, v19, v96, v27
	v_mul_f32_e32 v97, v97, v19
	v_fma_f32 v96, v20, v96, v28
	v_mul_f32_e32 v97, v97, v20
	v_fma_f32 v96, v21, v96, v29
	v_mul_f32_e32 v97, v97, v21
	v_fma_f32 v96, v22, v96, v30
	v_mul_f32_e32 v97, v97, v22
	v_fma_f32 v96, v23, v96, v31
	v_mul_f32_e32 v97, v97, v23
	s_waitcnt lgkmcnt(0)
; template <int PASS>
; __device__ __forceinline__ void lru_tile_phase(const Params& p, int jl, int Mrows, char* smem, int tid, int bid) {
;     ...
;       for (int i0 = 0; i0 < 64; i0 += 16) {
;         float av[16], uv[16];
; #pragma unroll
;         for (int k = 0; k < 16; ++k) { const int t = dir ? 63 - (i0 + k) : i0 + k; av[k] = ap_[t * 128]; uv[k] = up_[t * 128]; }
; #pragma unroll
;         for (int k = 0; k < 16; ++k) { hst = fmaf(av[k], hst, uv[k]); if (PASS == 1) ap *= av[k]; else uv[k] = hst; }
	ds_read2st64_b32 v[16:17], v188 offset0:48 offset1:50
	ds_read2st64_b32 v[18:19], v188 offset0:52 offset1:54
	ds_read2st64_b32 v[20:21], v188 offset0:56 offset1:58
	ds_read2st64_b32 v[22:23], v188 offset0:60 offset1:62
	ds_read2st64_b32 v[24:25], v195 offset0:48 offset1:50
	ds_read2st64_b32 v[26:27], v195 offset0:52 offset1:54
	ds_read2st64_b32 v[28:29], v195 offset0:56 offset1:58
	ds_read2st64_b32 v[30:31], v195 offset0:60 offset1:62
	v_fma_f32 v96, v0, v96, v8
	v_mul_f32_e32 v97, v97, v0
	v_fma_f32 v96, v1, v96, v9
	v_mul_f32_e32 v97, v97, v1
	v_fma_f32 v96, v2, v96, v10
	v_mul_f32_e32 v97, v97, v2
	v_fma_f32 v96, v3, v96, v11
	v_mul_f32_e32 v97, v97, v3
	v_fma_f32 v96, v4, v96, v12
	v_mul_f32_e32 v97, v97, v4
	v_fma_f32 v96, v5, v96, v13
	v_mul_f32_e32 v97, v97, v5
	v_fma_f32 v96, v6, v96, v14
	v_mul_f32_e32 v97, v97, v6
	v_fma_f32 v96, v7, v96, v15
	v_mul_f32_e32 v97, v97, v7
	s_waitcnt lgkmcnt(0)
	ds_read2st64_b32 v[0:1], v188 offset0:64 offset1:66
	ds_read2st64_b32 v[2:3], v188 offset0:68 offset1:70
	ds_read2st64_b32 v[4:5], v188 offset0:72 offset1:74
	ds_read2st64_b32 v[6:7], v188 offset0:76 offset1:78
	ds_read2st64_b32 v[8:9], v195 offset0:64 offset1:66
	ds_read2st64_b32 v[10:11], v195 offset0:68 offset1:70
	ds_read2st64_b32 v[12:13], v195 offset0:72 offset1:74
	ds_read2st64_b32 v[14:15], v195 offset0:76 offset1:78
	v_fma_f32 v96, v16, v96, v24
	v_mul_f32_e32 v97, v97, v16
	v_fma_f32 v96, v17, v96, v25
	v_mul_f32_e32 v97, v97, v17
	v_fma_f32 v96, v18, v96, v26
	v_mul_f32_e32 v97, v97, v18
	v_fma_f32 v96, v19, v96, v27
	v_mul_f32_e32 v97, v97, v19
	v_fma_f32 v96, v20, v96, v28
	v_mul_f32_e32 v97, v97, v20
	v_fma_f32 v96, v21, v96, v29
	v_mul_f32_e32 v97, v97, v21
	v_fma_f32 v96, v22, v96, v30
	v_mul_f32_e32 v97, v97, v22
	v_fma_f32 v96, v23, v96, v31
	v_mul_f32_e32 v97, v97, v23
	s_waitcnt lgkmcnt(0)
	ds_read2st64_b32 v[16:17], v188 offset0:80 offset1:82
	ds_read2st64_b32 v[18:19], v188 offset0:84 offset1:86
	ds_read2st64_b32 v[20:21], v188 offset0:88 offset1:90
	ds_read2st64_b32 v[22:23], v188 offset0:92 offset1:94
	ds_read2st64_b32 v[24:25], v195 offset0:80 offset1:82
	ds_read2st64_b32 v[26:27], v195 offset0:84 offset1:86
	ds_read2st64_b32 v[28:29], v195 offset0:88 offset1:90
	ds_read2st64_b32 v[30:31], v195 offset0:92 offset1:94
	v_fma_f32 v96, v0, v96, v8
	v_mul_f32_e32 v97, v97, v0
	v_fma_f32 v96, v1, v96, v9
	v_mul_f32_e32 v97, v97, v1
	v_fma_f32 v96, v2, v96, v10
	v_mul_f32_e32 v97, v97, v2
	v_fma_f32 v96, v3, v96, v11
	v_mul_f32_e32 v97, v97, v3
	v_fma_f32 v96, v4, v96, v12
	v_mul_f32_e32 v97, v97, v4
	v_fma_f32 v96, v5, v96, v13
	v_mul_f32_e32 v97, v97, v5
	v_fma_f32 v96, v6, v96, v14
	v_mul_f32_e32 v97, v97, v6
	v_fma_f32 v96, v7, v96, v15
	v_mul_f32_e32 v97, v97, v7
	s_waitcnt lgkmcnt(0)
	ds_read2st64_b32 v[0:1], v188 offset0:96 offset1:98
	ds_read2st64_b32 v[2:3], v188 offset0:100 offset1:102
	ds_read2st64_b32 v[4:5], v188 offset0:104 offset1:106
	ds_read2st64_b32 v[6:7], v188 offset0:108 offset1:110
	ds_read2st64_b32 v[8:9], v195 offset0:96 offset1:98
	ds_read2st64_b32 v[10:11], v195 offset0:100 offset1:102
	ds_read2st64_b32 v[12:13], v195 offset0:104 offset1:106
	ds_read2st64_b32 v[14:15], v195 offset0:108 offset1:110
	v_fma_f32 v96, v16, v96, v24
	v_mul_f32_e32 v97, v97, v16
	v_fma_f32 v96, v17, v96, v25
	v_mul_f32_e32 v97, v97, v17
	v_fma_f32 v96, v18, v96, v26
	v_mul_f32_e32 v97, v97, v18
	v_fma_f32 v96, v19, v96, v27
	v_mul_f32_e32 v97, v97, v19
	v_fma_f32 v96, v20, v96, v28
	v_mul_f32_e32 v97, v97, v20
	v_fma_f32 v96, v21, v96, v29
	v_mul_f32_e32 v97, v97, v21
	v_fma_f32 v96, v22, v96, v30
	v_mul_f32_e32 v97, v97, v22
	v_fma_f32 v96, v23, v96, v31
	v_mul_f32_e32 v97, v97, v23
	s_waitcnt lgkmcnt(0)
	ds_read2st64_b32 v[16:17], v188 offset0:112 offset1:114
	ds_read2st64_b32 v[18:19], v188 offset0:116 offset1:118
	ds_read2st64_b32 v[20:21], v188 offset0:120 offset1:122
	ds_read2st64_b32 v[22:23], v188 offset0:124 offset1:126
	ds_read2st64_b32 v[24:25], v195 offset0:112 offset1:114
	ds_read2st64_b32 v[26:27], v195 offset0:116 offset1:118
	ds_read2st64_b32 v[28:29], v195 offset0:120 offset1:122
	ds_read2st64_b32 v[30:31], v195 offset0:124 offset1:126
	v_fma_f32 v96, v0, v96, v8
	v_mul_f32_e32 v97, v97, v0
	v_fma_f32 v96, v1, v96, v9
	v_mul_f32_e32 v97, v97, v1
	v_fma_f32 v96, v2, v96, v10
	v_mul_f32_e32 v97, v97, v2
	v_fma_f32 v96, v3, v96, v11
	v_mul_f32_e32 v97, v97, v3
	v_fma_f32 v96, v4, v96, v12
	v_mul_f32_e32 v97, v97, v4
	v_fma_f32 v96, v5, v96, v13
	v_mul_f32_e32 v97, v97, v5
	v_fma_f32 v96, v6, v96, v14
	v_mul_f32_e32 v97, v97, v6
	v_fma_f32 v96, v7, v96, v15
	v_mul_f32_e32 v97, v97, v7
	s_waitcnt lgkmcnt(0)
	v_fma_f32 v96, v16, v96, v24
	v_mul_f32_e32 v97, v97, v16
	v_fma_f32 v96, v17, v96, v25
	v_mul_f32_e32 v97, v97, v17
	v_fma_f32 v96, v18, v96, v26
	v_mul_f32_e32 v97, v97, v18
	v_fma_f32 v96, v19, v96, v27
	v_mul_f32_e32 v97, v97, v19
	v_fma_f32 v96, v20, v96, v28
	v_mul_f32_e32 v97, v97, v20
	v_fma_f32 v96, v21, v96, v29
	v_mul_f32_e32 v97, v97, v21
	v_fma_f32 v96, v22, v96, v30
	v_mul_f32_e32 v97, v97, v22
	v_fma_f32 v96, v23, v96, v31
	v_mul_f32_e32 v97, v97, v23
	s_branch .Llru1_scan_store
